# v88 plus DPP / permlane butterfly reductions of the LN statistics in the J layer-0 loop
# baseline (speedup 1.0000x reference)
.LBB0_1743:
	v_mov_b32_e32 v2, v0
	s_mov_b64 s[8:9], s[44:45]
	v_mov_b32_e32 v1, v232
	s_mov_b64 s[34:35], s[46:47]
	s_mov_b64 s[10:11], s[0:1]
	s_add_i32 s8, s60, s30
	v_lshlrev_b32_e32 v2, 2, v1
	s_waitcnt lgkmcnt(0)
	v_ashrrev_i32_e32 v3, 31, v2
	v_lshlrev_b64 v[4:5], 1, v[2:3]
	v_lshl_add_u64 v[6:7], s[34:35], 0, v[4:5]
	v_lshl_add_u64 v[32:33], v[6:7], 0, s[24:25]
	global_load_dwordx2 v[6:7], v[32:33], off offset:-3584
	global_load_dwordx2 v[34:35], v[32:33], off offset:-3072
	global_load_dwordx2 v[44:45], v[32:33], off offset:-2560
	global_load_dwordx2 v[8:9], v[32:33], off offset:-2048
	s_cmpk_lt_i32 s8, 0x2000
	s_cselect_b32 s36, s8, s30
	s_add_u32 s18, s34, 0x28c000
	s_addc_u32 s19, s35, 0
	s_ashr_i32 s37, s36, 31
	s_ashr_i32 s31, s30, 31
	s_lshl_b64 s[8:9], s[36:37], 12
	s_add_u32 s16, s34, s8
	s_addc_u32 s17, s35, s9
	v_lshl_add_u64 v[4:5], s[16:17], 0, v[4:5]
	s_mov_b64 s[8:9], 0x1d91e000
	v_lshl_add_u64 v[224:225], v[4:5], 0, s[8:9]
	global_load_dwordx2 v[118:119], v[224:225], off
	global_load_dwordx2 v[120:121], v[224:225], off offset:512
	global_load_dwordx2 v[122:123], v[224:225], off offset:1024
	global_load_dwordx2 v[144:145], v[224:225], off offset:1536
	global_load_dwordx2 v[146:147], v[224:225], off offset:2048
	global_load_dwordx2 v[152:153], v[224:225], off offset:2560
	global_load_dwordx2 v[154:155], v[224:225], off offset:3072
	global_load_dwordx2 v[234:235], v[224:225], off offset:3584
	v_and_b32_e32 v14, 64, v249
	v_add_u32_e32 v14, 64, v14
	v_xor_b32_e32 v20, 1, v249
	v_lshlrev_b64 v[86:87], 2, v[2:3]
	s_add_u32 s20, s34, 0x28e000
	s_addc_u32 s21, s35, 0
	v_lshl_add_u64 v[88:89], s[20:21], 0, v[86:87]
	s_add_u32 s58, s34, 0x1515b000
	s_addc_u32 s59, s35, 0
	s_waitcnt vmcnt(3)
	v_lshlrev_b32_e32 v68, 16, v6
	s_waitcnt vmcnt(2)
	v_lshlrev_b32_e32 v69, 16, v34
	v_and_b32_e32 v75, 0xffff0000, v34
	s_waitcnt vmcnt(0)
	v_lshlrev_b32_e32 v36, 16, v8
	v_and_b32_e32 v37, 0xffff0000, v8
	v_lshlrev_b32_e32 v38, 16, v9
	v_and_b32_e32 v39, 0xffff0000, v9
	global_load_dwordx2 v[8:9], v[32:33], off offset:-1536
	v_and_b32_e32 v74, 0xffff0000, v6
	v_and_b32_e32 v73, 0xffff0000, v35
	v_and_b32_e32 v72, 0xffff0000, v7
	v_lshlrev_b32_e32 v34, 16, v44
	v_add_f32_e32 v66, v36, v37
	v_add_f32_e32 v46, v38, v39
	s_waitcnt vmcnt(0)
	v_lshlrev_b32_e32 v43, 16, v8
	v_and_b32_e32 v41, 0xffff0000, v8
	v_lshlrev_b32_e32 v67, 16, v9
	v_and_b32_e32 v47, 0xffff0000, v9
	global_load_dwordx2 v[70:71], v[32:33], off offset:-1024
	global_load_dwordx2 v[8:9], v[32:33], off offset:-512
	s_waitcnt vmcnt(0)
	v_lshlrev_b32_e32 v48, 16, v8
	v_and_b32_e32 v49, 0xffff0000, v8
	v_lshlrev_b32_e32 v50, 16, v9
	v_and_b32_e32 v51, 0xffff0000, v9
	global_load_dwordx2 v[8:9], v[32:33], off
	v_add_f32_e32 v64, v48, v49
	v_add_f32_e32 v54, v50, v51
	s_waitcnt vmcnt(0)
	v_lshlrev_b32_e32 v52, 16, v8
	v_and_b32_e32 v53, 0xffff0000, v8
	v_lshlrev_b32_e32 v65, 16, v9
	v_and_b32_e32 v55, 0xffff0000, v9
	v_lshl_add_u64 v[8:9], v[4:5], 0, s[8:9]
	s_mov_b32 s8, 0x1d91e000
	v_add_co_u32_e32 v4, vcc, s8, v4
	s_nop 1
	v_addc_co_u32_e32 v5, vcc, 0, v5, vcc
	s_nop 1
	v_mov_b64_e32 v[60:61], v[118:119]
	s_nop 1
	v_mov_b64_e32 v[62:63], v[120:121]
	s_nop 1
	v_mov_b64_e32 v[58:59], v[122:123]
	s_nop 0
	s_nop 1
	v_mov_b64_e32 v[4:5], v[144:145]
	v_cmp_lt_i32_e32 vcc, v20, v14
	s_waitcnt vmcnt(0)
	v_lshlrev_b32_e32 v28, 16, v4
	v_and_b32_e32 v29, 0xffff0000, v4
	v_lshlrev_b32_e32 v30, 16, v5
	v_and_b32_e32 v31, 0xffff0000, v5
	s_nop 1
	v_mov_b64_e32 v[4:5], v[146:147]
	v_cndmask_b32_e32 v20, v249, v20, vcc
	v_lshlrev_b32_e32 v90, 2, v20
	v_add_f32_e32 v26, v28, v29
	v_add_f32_e32 v24, v30, v31
	s_waitcnt vmcnt(0)
	v_lshlrev_b32_e32 v23, 16, v4
	v_and_b32_e32 v21, 0xffff0000, v4
	v_lshlrev_b32_e32 v27, 16, v5
	v_and_b32_e32 v25, 0xffff0000, v5
	s_nop 1
	v_mov_b64_e32 v[56:57], v[152:153]
	s_nop 1
	v_mov_b64_e32 v[4:5], v[154:155]
	s_load_dwordx4 s[12:15], s[10:11], 0xb0
	s_load_dwordx2 s[38:39], s[10:11], 0x68
	s_waitcnt lgkmcnt(0)
	v_lshl_add_u64 v[84:85], s[12:13], 0, v[86:87]
	s_waitcnt vmcnt(0)
	v_lshlrev_b32_e32 v16, 16, v4
	v_and_b32_e32 v17, 0xffff0000, v4
	v_lshlrev_b32_e32 v18, 16, v5
	v_and_b32_e32 v19, 0xffff0000, v5
	s_nop 1
	v_mov_b64_e32 v[4:5], v[234:235]
	v_lshlrev_b32_e32 v9, 16, v35
	v_lshlrev_b32_e32 v8, 16, v7
	v_pk_add_f32 v[6:7], v[8:9], v[72:73]
	v_lshlrev_b32_e32 v35, 16, v45
	s_waitcnt vmcnt(0)
	v_lshlrev_b32_e32 v10, 16, v4
	v_and_b32_e32 v11, 0xffff0000, v4
	v_lshlrev_b32_e32 v15, 16, v5
	v_and_b32_e32 v13, 0xffff0000, v5
	v_pk_add_f32 v[4:5], v[68:69], v[74:75]
	s_nop 0
	v_pk_add_f32 v[4:5], v[4:5], v[6:7]
	v_and_b32_e32 v7, 0xffff0000, v45
	v_add_f32_e32 v4, 0, v4
	v_and_b32_e32 v6, 0xffff0000, v44
	v_add_f32_e32 v42, v4, v5
	v_pk_add_f32 v[4:5], v[34:35], v[6:7]
	v_pk_add_f32 v[44:45], v[66:67], v[46:47]
	v_pk_add_f32 v[4:5], v[4:5], v[4:5] op_sel:[0,1] op_sel_hi:[1,0]
	s_nop 0
	v_mov_b32_e32 v5, v41
	v_pk_add_f32 v[4:5], v[42:43], v[4:5]
	s_nop 0
	v_pk_add_f32 v[76:77], v[4:5], v[44:45]
	v_lshlrev_b32_e32 v45, 16, v71
	v_lshlrev_b32_e32 v44, 16, v70
	v_and_b32_e32 v5, 0xffff0000, v71
	v_and_b32_e32 v4, 0xffff0000, v70
	v_pk_add_f32 v[70:71], v[44:45], v[4:5]
	v_pk_add_f32 v[76:77], v[76:77], v[76:77] op_sel:[0,1] op_sel_hi:[1,0]
	v_pk_add_f32 v[70:71], v[70:71], v[70:71] op_sel:[0,1] op_sel_hi:[1,0]
	v_mov_b32_e32 v77, v52
	v_mov_b32_e32 v71, v53
	v_pk_add_f32 v[70:71], v[76:77], v[70:71]
	v_pk_add_f32 v[76:77], v[64:65], v[54:55]
	s_nop 0
	v_pk_add_f32 v[70:71], v[70:71], v[76:77]
	s_nop 0
	v_add_f32_e32 v12, v70, v71
	s_nop 1
	v_mov_b32_dpp v20, v12 quad_perm:[1,0,3,2] row_mask:0xf bank_mask:0xf
	s_waitcnt lgkmcnt(0)
	v_add_f32_e32 v12, v12, v20
	v_xor_b32_e32 v20, 2, v249
	v_cmp_lt_i32_e32 vcc, v20, v14
	s_nop 1
	v_cndmask_b32_e32 v20, v249, v20, vcc
	v_lshlrev_b32_e32 v91, 2, v20
	s_nop 1
	v_mov_b32_dpp v20, v12 quad_perm:[2,3,0,1] row_mask:0xf bank_mask:0xf
	s_waitcnt lgkmcnt(0)
	v_add_f32_e32 v12, v12, v20
	v_xor_b32_e32 v20, 4, v249
	v_cmp_lt_i32_e32 vcc, v20, v14
	s_nop 1
	v_cndmask_b32_e32 v20, v249, v20, vcc
	v_lshlrev_b32_e32 v92, 2, v20
	s_nop 1
	v_mov_b32_dpp v20, v12 row_half_mirror row_mask:0xf bank_mask:0xf
	s_waitcnt lgkmcnt(0)
	v_add_f32_e32 v12, v12, v20
	v_xor_b32_e32 v20, 8, v249
	v_cmp_lt_i32_e32 vcc, v20, v14
	s_nop 1
	v_cndmask_b32_e32 v20, v249, v20, vcc
	v_lshlrev_b32_e32 v93, 2, v20
	s_nop 1
	v_mov_b32_dpp v20, v12 row_mirror row_mask:0xf bank_mask:0xf
	s_waitcnt lgkmcnt(0)
	v_add_f32_e32 v12, v12, v20
	v_xor_b32_e32 v20, 16, v249
	v_cmp_lt_i32_e32 vcc, v20, v14
	s_nop 1
	v_cndmask_b32_e32 v20, v249, v20, vcc
	v_lshlrev_b32_e32 v94, 2, v20
	v_mov_b32_e32 v20, v12
	v_mov_b32_e32 v139, v12
	s_nop 1
	v_permlane16_swap_b32_e32 v20, v139
	s_waitcnt lgkmcnt(0)
	s_nop 1
	v_add_f32_e32 v12, v20, v139
	v_xor_b32_e32 v20, 32, v249
	v_cmp_lt_i32_e32 vcc, v20, v14
	s_nop 1
	v_cndmask_b32_e32 v14, v249, v20, vcc
	v_lshlrev_b32_e32 v95, 2, v14
	v_mov_b32_e32 v14, v12
	v_mov_b32_e32 v139, v12
	s_nop 1
	v_permlane32_swap_b32_e32 v14, v139
	s_waitcnt lgkmcnt(0)
	s_nop 1
	v_add_f32_e32 v12, v14, v139
	v_fmac_f32_e32 v74, 0xba000000, v12
	v_fmac_f32_e32 v75, 0xba000000, v12
	v_fmac_f32_e32 v72, 0xba000000, v12
	v_fmac_f32_e32 v68, 0xba000000, v12
	v_fmac_f32_e32 v73, 0xba000000, v12
	v_fmac_f32_e32 v69, 0xba000000, v12
	v_mov_b32_e32 v71, v75
	v_mov_b32_e32 v77, v74
	v_pk_mul_f32 v[74:75], v[74:75], v[74:75]
	v_fmac_f32_e32 v8, 0xba000000, v12
	v_fmac_f32_e32 v9, 0xba000000, v12
	v_mov_b32_e32 v70, v69
	v_mov_b32_e32 v76, v68
	v_pk_fma_f32 v[68:69], v[68:69], v[68:69], v[74:75]
	v_mov_b32_e32 v75, v73
	v_mov_b32_e32 v79, v72
	v_pk_mul_f32 v[72:73], v[72:73], v[72:73]
	v_fmac_f32_e32 v6, 0xba000000, v12
	v_fmac_f32_e32 v7, 0xba000000, v12
	v_fmac_f32_e32 v35, 0xba000000, v12
	v_mov_b32_e32 v74, v9
	v_mov_b32_e32 v78, v8
	v_pk_fma_f32 v[8:9], v[8:9], v[8:9], v[72:73]
	v_fmac_f32_e32 v34, 0xba000000, v12
	v_mov_b32_e32 v72, v35
	v_mov_b32_e32 v73, v7
	v_mov_b32_e32 v35, v6
	v_pk_add_f32 v[8:9], v[68:69], v[8:9]
	v_pk_mul_f32 v[68:69], v[72:73], v[72:73]
	v_pk_mul_f32 v[6:7], v[34:35], v[34:35]
	v_fmac_f32_e32 v36, 0xba000000, v12
	v_pk_mov_b32 v[80:81], v[6:7], v[68:69] op_sel:[1,0]
	v_mov_b32_e32 v7, v69
	v_pk_add_f32 v[6:7], v[80:81], v[6:7]
	v_fmac_f32_e32 v37, 0xba000000, v12
	v_pk_add_f32 v[6:7], v[6:7], v[6:7] op_sel_hi:[0,1]
	v_fmac_f32_e32 v38, 0xba000000, v12
	v_mul_f32_e32 v6, v36, v36
	v_fmac_f32_e32 v39, 0xba000000, v12
	v_pk_fma_f32 v[68:69], v[36:37], v[36:37], v[6:7] op_sel_hi:[1,1,0]
	v_mul_f32_e32 v6, v38, v38
	v_pk_add_f32 v[8:9], v[8:9], v[8:9] op_sel_hi:[0,1]
	v_pk_fma_f32 v[80:81], v[38:39], v[38:39], v[6:7] op_sel_hi:[1,1,0]
	v_fmac_f32_e32 v47, 0xba000000, v12
	v_fmac_f32_e32 v67, 0xba000000, v12
	v_fmac_f32_e32 v41, 0xba000000, v12
	v_fmac_f32_e32 v43, 0xba000000, v12
	v_mul_f32_e32 v68, v43, v43
	v_mul_f32_e32 v80, v41, v41
	v_mul_f32_e32 v6, v67, v67
	v_mul_f32_e32 v8, v47, v47
	v_pk_add_f32 v[68:69], v[68:69], v[80:81]
	v_pk_add_f32 v[6:7], v[6:7], v[8:9]
	v_fmac_f32_e32 v4, 0xba000000, v12
	v_fmac_f32_e32 v5, 0xba000000, v12
	v_fmac_f32_e32 v45, 0xba000000, v12
	v_pk_add_f32 v[6:7], v[68:69], v[6:7]
	v_fmac_f32_e32 v44, 0xba000000, v12
	v_mov_b32_e32 v68, v45
	v_mov_b32_e32 v69, v5
	v_mov_b32_e32 v45, v4
	v_pk_mul_f32 v[8:9], v[68:69], v[68:69]
	v_pk_mul_f32 v[4:5], v[44:45], v[44:45]
	v_fmac_f32_e32 v48, 0xba000000, v12
	v_pk_mov_b32 v[80:81], v[4:5], v[8:9] op_sel:[1,0]
	v_mov_b32_e32 v5, v9
	v_pk_add_f32 v[4:5], v[80:81], v[4:5]
	v_fmac_f32_e32 v49, 0xba000000, v12
	v_pk_add_f32 v[4:5], v[4:5], v[4:5] op_sel_hi:[0,1]
	v_fmac_f32_e32 v50, 0xba000000, v12
	v_mul_f32_e32 v4, v48, v48
	v_fmac_f32_e32 v51, 0xba000000, v12
	v_pk_fma_f32 v[8:9], v[48:49], v[48:49], v[4:5] op_sel_hi:[1,1,0]
	v_mul_f32_e32 v4, v50, v50
	v_pk_add_f32 v[6:7], v[6:7], v[6:7] op_sel_hi:[0,1]
	v_pk_fma_f32 v[80:81], v[50:51], v[50:51], v[4:5] op_sel_hi:[1,1,0]
	v_fmac_f32_e32 v55, 0xba000000, v12
	v_fmac_f32_e32 v65, 0xba000000, v12
	v_fmac_f32_e32 v53, 0xba000000, v12
	v_fmac_f32_e32 v52, 0xba000000, v12
	v_mul_f32_e32 v8, v52, v52
	v_mul_f32_e32 v80, v53, v53
	v_mul_f32_e32 v4, v65, v65
	v_mul_f32_e32 v6, v55, v55
	v_pk_add_f32 v[8:9], v[8:9], v[80:81]
	v_pk_add_f32 v[4:5], v[4:5], v[6:7]
	v_lshl_add_u64 v[80:81], s[14:15], 0, v[86:87]
	v_pk_add_f32 v[4:5], v[8:9], v[4:5]
	v_mov_b32_e32 v46, v67
	v_add_f32_e32 v4, v4, v5
	s_nop 1
	v_mov_b32_dpp v5, v4 quad_perm:[1,0,3,2] row_mask:0xf bank_mask:0xf
	v_mov_b32_e32 v40, v43
	v_mov_b32_e32 v54, v65
	s_waitcnt lgkmcnt(0)
	v_add_f32_e32 v4, v4, v5
	s_nop 1
	v_mov_b32_dpp v5, v4 quad_perm:[2,3,0,1] row_mask:0xf bank_mask:0xf
	s_waitcnt lgkmcnt(0)
	v_add_f32_e32 v4, v4, v5
	s_nop 1
	v_mov_b32_dpp v5, v4 row_half_mirror row_mask:0xf bank_mask:0xf
	s_waitcnt lgkmcnt(0)
	v_add_f32_e32 v4, v4, v5
	s_nop 1
	v_mov_b32_dpp v5, v4 row_mirror row_mask:0xf bank_mask:0xf
	s_waitcnt lgkmcnt(0)
	v_add_f32_e32 v4, v4, v5
	v_mov_b32_e32 v5, v4
	v_mov_b32_e32 v139, v4
	s_nop 1
	v_permlane16_swap_b32_e32 v5, v139
	s_waitcnt lgkmcnt(0)
	s_nop 1
	v_add_f32_e32 v4, v5, v139
	v_mov_b32_e32 v5, v4
	v_mov_b32_e32 v139, v4
	s_nop 1
	v_permlane32_swap_b32_e32 v5, v139
	s_waitcnt lgkmcnt(0)
	s_nop 1
	v_add_f32_e32 v4, v5, v139
	v_fmamk_f32 v4, v4, 0x3a000000, v250
	v_cmp_gt_f32_e32 vcc, s96, v4
	v_mul_f32_e32 v5, 0x4f800000, v4
	s_nop 0
	v_cndmask_b32_e32 v4, v4, v5, vcc
	v_sqrt_f32_e32 v5, v4
	s_nop 0
	v_add_u32_e32 v6, -1, v5
	v_fma_f32 v7, -v6, v5, v4
	v_cmp_ge_f32_e64 s[10:11], 0, v7
	v_add_u32_e32 v7, 1, v5
	s_nop 0
	v_cndmask_b32_e64 v6, v5, v6, s[10:11]
	v_fma_f32 v5, -v7, v5, v4
	v_cmp_lt_f32_e64 s[10:11], 0, v5
	s_nop 1
	v_cndmask_b32_e64 v5, v6, v7, s[10:11]
	v_mul_f32_e32 v6, 0x37800000, v5
	v_cndmask_b32_e32 v5, v5, v6, vcc
	v_cmp_class_f32_e32 vcc, v4, v251
	s_nop 1
	v_cndmask_b32_e32 v4, v5, v4, vcc
	v_div_scale_f32 v5, s[8:9], v4, v4, 1.0
	v_rcp_f32_e32 v6, v5
	s_movk_i32 s8, 0xf000
	v_fma_f32 v7, -v5, v6, 1.0
	v_fmac_f32_e32 v6, v7, v6
	v_div_scale_f32 v7, vcc, 1.0, v4, 1.0
	v_mul_f32_e32 v8, v7, v6
	v_fma_f32 v9, -v5, v8, v7
	v_fmac_f32_e32 v8, v9, v6
	v_fma_f32 v5, -v5, v8, v7
	v_div_fmas_f32 v5, v5, v6, v8
	v_div_fixup_f32 v12, v5, v4, 1.0
	s_nop 1
	v_mov_b64_e32 v[2:3], v[180:181]
	v_mov_b64_e32 v[4:5], v[182:183]
	s_nop 1
	v_mov_b64_e32 v[6:7], v[212:213]
	v_mov_b64_e32 v[8:9], v[214:215]
	v_pk_mul_f32 v[76:77], v[76:77], v[12:13] op_sel_hi:[1,0]
	v_pk_mul_f32 v[78:79], v[78:79], v[12:13] op_sel_hi:[1,0]
	v_pk_mul_f32 v[70:71], v[70:71], v[12:13] op_sel_hi:[1,0]
	v_pk_mul_f32 v[34:35], v[34:35], v[12:13] op_sel_hi:[1,0]
	v_pk_mul_f32 v[38:39], v[38:39], v[12:13] op_sel_hi:[1,0]
	v_pk_mul_f32 v[36:37], v[36:37], v[12:13] op_sel_hi:[1,0]
	v_pk_mul_f32 v[46:47], v[46:47], v[12:13] op_sel_hi:[1,0]
	v_pk_mul_f32 v[40:41], v[40:41], v[12:13] op_sel_hi:[1,0]
	v_pk_mul_f32 v[44:45], v[44:45], v[12:13] op_sel_hi:[1,0]
	v_pk_mul_f32 v[50:51], v[50:51], v[12:13] op_sel_hi:[1,0]
	v_pk_mul_f32 v[48:49], v[48:49], v[12:13] op_sel_hi:[1,0]
	v_pk_mul_f32 v[54:55], v[54:55], v[12:13] op_sel_hi:[1,0]
	v_pk_mul_f32 v[52:53], v[52:53], v[12:13] op_sel_hi:[1,0]
	s_waitcnt vmcnt(0)
	v_pk_fma_f32 v[6:7], v[2:3], v[76:77], v[6:7]
	v_lshl_add_u64 v[2:3], s[34:35], 0, v[86:87]
	v_lshl_add_u64 v[76:77], v[2:3], 0, s[22:23]
	v_add_co_u32_e32 v104, vcc, s8, v76
	v_pk_fma_f32 v[8:9], v[4:5], v[78:79], v[8:9]
	s_nop 0
	v_addc_co_u32_e32 v105, vcc, -1, v77, vcc
	global_store_dwordx4 v[104:105], v[6:9], off offset:-3072
	ds_read_b128 v[2:5], v127
	v_lshl_add_u64 v[86:87], s[18:19], 0, v[86:87]
	ds_read_b128 v[96:99], v127 offset:8192
	s_mov_b32 s8, 0xef2fd000
	s_waitcnt lgkmcnt(0)
	v_pk_add_f32 v[4:5], v[4:5], 1.0 op_sel_hi:[1,0]
	v_pk_add_f32 v[78:79], v[2:3], 1.0 op_sel_hi:[1,0]
	s_nop 0
	v_pk_fma_f32 v[2:3], v[4:5], v[8:9], v[98:99]
	v_pk_fma_f32 v[4:5], v[78:79], v[6:7], v[96:97]
	s_nop 0
	s_nop 0
	s_nop 0
	s_nop 0
	s_nop 0
	s_nop 0
	v_cvt_pk_bf16_f32 v6, v4, v5
	s_nop 0
	s_nop 0
	s_nop 0
	s_nop 0
	v_add_co_u32_e32 v78, vcc, s8, v32
	v_cvt_pk_bf16_f32 v7, v2, v3
	s_nop 0
	v_addc_co_u32_e32 v79, vcc, -1, v33, vcc
	global_store_dwordx2 v[78:79], v[6:7], off offset:-3584
	s_nop 1
	v_mov_b64_e32 v[6:7], v[184:185]
	v_mov_b64_e32 v[8:9], v[186:187]
	s_nop 0
	s_nop 1
	v_mov_b64_e32 v[96:97], v[216:217]
	v_mov_b64_e32 v[98:99], v[218:219]
	v_pk_mul_f32 v[32:33], v[74:75], v[12:13] op_sel_hi:[1,0]
	s_lshl_b64 s[8:9], s[36:37], 13
	s_add_u32 s40, s34, s8
	s_addc_u32 s41, s35, s9
	s_waitcnt vmcnt(0)
	v_pk_fma_f32 v[96:97], v[6:7], v[70:71], v[96:97]
	v_pk_fma_f32 v[98:99], v[8:9], v[32:33], v[98:99]
	global_store_dwordx4 v[104:105], v[96:99], off offset:-2048
	ds_read_b128 v[6:9], v127 offset:1024
	ds_read_b128 v[100:103], v127 offset:9216
	s_waitcnt lgkmcnt(0)
	v_pk_add_f32 v[8:9], v[8:9], 1.0 op_sel_hi:[1,0]
	v_pk_add_f32 v[32:33], v[6:7], 1.0 op_sel_hi:[1,0]
	s_nop 0
	v_pk_fma_f32 v[6:7], v[8:9], v[98:99], v[102:103]
	v_pk_fma_f32 v[8:9], v[32:33], v[96:97], v[100:101]
	s_nop 0
	s_nop 0
	s_nop 0
	s_nop 0
	s_nop 0
	s_nop 0
	v_cvt_pk_bf16_f32 v32, v8, v9
	s_nop 0
	s_nop 0
	s_nop 0
	s_nop 0
	s_nop 0
	v_cvt_pk_bf16_f32 v33, v6, v7
	global_store_dwordx2 v[78:79], v[32:33], off offset:-3072
	s_nop 1
	v_mov_b64_e32 v[96:97], v[188:189]
	v_mov_b64_e32 v[98:99], v[190:191]
	s_nop 1
	v_mov_b64_e32 v[100:101], v[220:221]
	v_mov_b64_e32 v[102:103], v[222:223]
	v_pk_mul_f32 v[32:33], v[72:73], v[12:13] op_sel_hi:[1,0]
	s_waitcnt vmcnt(0)
	v_pk_fma_f32 v[70:71], v[96:97], v[34:35], v[100:101]
	v_pk_fma_f32 v[72:73], v[98:99], v[32:33], v[102:103]
	global_store_dwordx4 v[104:105], v[70:73], off offset:-1024
	ds_read_b128 v[32:35], v127 offset:2048
	ds_read_b128 v[96:99], v127 offset:10240
	s_waitcnt lgkmcnt(0)
	v_pk_add_f32 v[34:35], v[34:35], 1.0 op_sel_hi:[1,0]
	v_pk_add_f32 v[74:75], v[32:33], 1.0 op_sel_hi:[1,0]
	s_nop 0
	v_pk_fma_f32 v[32:33], v[34:35], v[72:73], v[98:99]
	v_pk_fma_f32 v[34:35], v[74:75], v[70:71], v[96:97]
	s_nop 0
	s_nop 0
	s_nop 0
	s_nop 0
	s_nop 0
	s_nop 0
	v_cvt_pk_bf16_f32 v70, v34, v35
	s_nop 0
	s_nop 0
	s_nop 0
	s_nop 0
	s_nop 0
	v_cvt_pk_bf16_f32 v71, v32, v33
	global_store_dwordx2 v[78:79], v[70:71], off offset:-2560
	s_nop 1
	v_mov_b64_e32 v[70:71], v[192:193]
	v_mov_b64_e32 v[72:73], v[194:195]
	s_nop 0
	s_nop 1
	v_mov_b64_e32 v[96:97], v[236:237]
	v_mov_b64_e32 v[98:99], v[238:239]
	s_waitcnt vmcnt(0)
	v_pk_fma_f32 v[70:71], v[70:71], v[36:37], v[96:97]
	v_pk_fma_f32 v[72:73], v[72:73], v[38:39], v[98:99]
	global_store_dwordx4 v[76:77], v[70:73], off offset:-4096
	ds_read_b128 v[36:39], v127 offset:3072
	ds_read_b128 v[96:99], v127 offset:11264
	s_waitcnt lgkmcnt(0)
	v_pk_add_f32 v[38:39], v[38:39], 1.0 op_sel_hi:[1,0]
	v_pk_add_f32 v[74:75], v[36:37], 1.0 op_sel_hi:[1,0]
	s_nop 0
	v_pk_fma_f32 v[36:37], v[38:39], v[72:73], v[98:99]
	v_pk_fma_f32 v[38:39], v[74:75], v[70:71], v[96:97]
	s_nop 0
	s_nop 0
	s_nop 0
	s_nop 0
	s_nop 0
	s_nop 0
	v_cvt_pk_bf16_f32 v70, v38, v39
	s_nop 0
	s_nop 0
	s_nop 0
	s_nop 0
	s_nop 0
	v_cvt_pk_bf16_f32 v71, v36, v37
	global_store_dwordx2 v[78:79], v[70:71], off offset:-2048
	v_add_co_u32_e32 v70, vcc, s82, v84
	s_nop 1
	v_addc_co_u32_e32 v71, vcc, 0, v85, vcc
	v_add_co_u32_e32 v72, vcc, s82, v80
	s_nop 1
	v_mov_b64_e32 v[96:97], v[196:197]
	v_mov_b64_e32 v[98:99], v[198:199]
	s_nop 0
	v_addc_co_u32_e32 v73, vcc, 0, v81, vcc
	s_nop 1
	v_mov_b64_e32 v[100:101], v[240:241]
	v_mov_b64_e32 v[102:103], v[242:243]
	v_add_co_u32_e32 v66, vcc, s82, v88
	s_waitcnt vmcnt(0)
	v_pk_fma_f32 v[96:97], v[40:41], v[96:97], v[100:101]
	v_pk_fma_f32 v[98:99], v[46:47], v[98:99], v[102:103]
	v_addc_co_u32_e32 v67, vcc, 0, v89, vcc
	global_store_dwordx4 v[76:77], v[96:99], off offset:-3072
	v_add_co_u32_e32 v80, vcc, s82, v86
	ds_read_b128 v[40:43], v127 offset:4096
	s_nop 0
	v_addc_co_u32_e32 v81, vcc, 0, v87, vcc
	ds_read_b128 v[84:87], v127 offset:12288
	s_waitcnt lgkmcnt(0)
	v_pk_add_f32 v[42:43], v[42:43], 1.0 op_sel_hi:[1,0]
	v_pk_add_f32 v[46:47], v[40:41], 1.0 op_sel_hi:[1,0]
	s_nop 0
	v_pk_fma_f32 v[40:41], v[98:99], v[42:43], v[86:87]
	v_pk_fma_f32 v[42:43], v[96:97], v[46:47], v[84:85]
	s_nop 0
	s_nop 0
	s_nop 0
	s_nop 0
	s_nop 0
	s_nop 0
	v_cvt_pk_bf16_f32 v46, v42, v43
	s_nop 0
	s_nop 0
	s_nop 0
	s_nop 0
	s_nop 0
	v_cvt_pk_bf16_f32 v47, v40, v41
	global_store_dwordx2 v[78:79], v[46:47], off offset:-1536
	s_nop 1
	v_mov_b64_e32 v[84:85], v[200:201]
	v_mov_b64_e32 v[86:87], v[202:203]
	s_nop 1
	v_mov_b64_e32 v[96:97], v[128:129]
	v_mov_b64_e32 v[98:99], v[130:131]
	v_pk_mul_f32 v[46:47], v[68:69], v[12:13] op_sel_hi:[1,0]
	s_waitcnt vmcnt(0)
	v_pk_fma_f32 v[84:85], v[44:45], v[84:85], v[96:97]
	v_pk_fma_f32 v[86:87], v[46:47], v[86:87], v[98:99]
	global_store_dwordx4 v[76:77], v[84:87], off offset:-2048
	ds_read_b128 v[44:47], v127 offset:5120
	ds_read_b128 v[96:99], v127 offset:13312
	s_waitcnt lgkmcnt(0)
	v_pk_add_f32 v[46:47], v[46:47], 1.0 op_sel_hi:[1,0]
	v_pk_add_f32 v[68:69], v[44:45], 1.0 op_sel_hi:[1,0]
	s_nop 0
	v_pk_fma_f32 v[44:45], v[86:87], v[46:47], v[98:99]
	v_pk_fma_f32 v[46:47], v[84:85], v[68:69], v[96:97]
	s_nop 0
	s_nop 0
	s_nop 0
	s_nop 0
	s_nop 0
	s_nop 0
	v_cvt_pk_bf16_f32 v68, v46, v47
	s_nop 0
	s_nop 0
	s_nop 0
	s_nop 0
	s_nop 0
	v_cvt_pk_bf16_f32 v69, v44, v45
	global_store_dwordx2 v[78:79], v[68:69], off offset:-1024
	s_nop 1
	v_mov_b64_e32 v[84:85], v[204:205]
	v_mov_b64_e32 v[86:87], v[206:207]
	s_nop 1
	v_mov_b64_e32 v[96:97], v[132:133]
	v_mov_b64_e32 v[98:99], v[134:135]
	s_waitcnt vmcnt(0)
	v_pk_fma_f32 v[84:85], v[48:49], v[84:85], v[96:97]
	v_pk_fma_f32 v[86:87], v[50:51], v[86:87], v[98:99]
	global_store_dwordx4 v[76:77], v[84:87], off offset:-1024
	ds_read_b128 v[48:51], v127 offset:6144
	ds_read_b128 v[96:99], v127 offset:14336
	s_waitcnt lgkmcnt(0)
	v_pk_add_f32 v[50:51], v[50:51], 1.0 op_sel_hi:[1,0]
	v_pk_add_f32 v[68:69], v[48:49], 1.0 op_sel_hi:[1,0]
	s_nop 0
	v_pk_fma_f32 v[48:49], v[86:87], v[50:51], v[98:99]
	v_pk_fma_f32 v[50:51], v[84:85], v[68:69], v[96:97]
	s_nop 0
	s_nop 0
	s_nop 0
	s_nop 0
	s_nop 0
	s_nop 0
	v_cvt_pk_bf16_f32 v68, v50, v51
	s_nop 0
	s_nop 0
	s_nop 0
	s_nop 0
	s_nop 0
	v_cvt_pk_bf16_f32 v69, v48, v49
	global_store_dwordx2 v[78:79], v[68:69], off offset:-512
	s_nop 1
	v_mov_b64_e32 v[68:69], v[208:209]
	v_mov_b64_e32 v[70:71], v[210:211]
	s_nop 0
	s_nop 1
	v_mov_b64_e32 v[72:73], v[140:141]
	v_mov_b64_e32 v[74:75], v[142:143]
	s_waitcnt vmcnt(0)
	v_pk_fma_f32 v[68:69], v[52:53], v[68:69], v[72:73]
	v_pk_fma_f32 v[70:71], v[54:55], v[70:71], v[74:75]
	global_store_dwordx4 v[76:77], v[68:71], off
	ds_read_b128 v[52:55], v127 offset:7168
	s_nop 0
	global_load_dwordx4 v[64:67], v[80:81], off offset:3072
	v_and_b32_e32 v77, 0xffff0000, v63
	v_and_b32_e32 v76, 0xffff0000, v61
	v_and_b32_e32 v75, 0xffff0000, v59
	v_and_b32_e32 v74, 0xffff0000, v58
	s_waitcnt vmcnt(0) lgkmcnt(0)
	v_pk_add_f32 v[54:55], v[54:55], 1.0 op_sel_hi:[1,0]
	v_pk_add_f32 v[72:73], v[52:53], 1.0 op_sel_hi:[1,0]
	s_nop 0
	v_pk_fma_f32 v[52:53], v[70:71], v[54:55], v[66:67]
	v_pk_fma_f32 v[54:55], v[68:69], v[72:73], v[64:65]
	v_and_b32_e32 v67, 0xffff0000, v62
	v_cvt_pk_bf16_f32 v64, v54, v55
	v_cvt_pk_bf16_f32 v65, v52, v53
	global_store_dwordx2 v[78:79], v[64:65], off
	v_lshlrev_b32_e32 v64, 16, v60
	v_lshlrev_b32_e32 v65, 16, v62
	v_and_b32_e32 v66, 0xffff0000, v60
	v_lshlrev_b32_e32 v70, 16, v61
	v_lshlrev_b32_e32 v71, 16, v63
	v_pk_add_f32 v[60:61], v[64:65], v[66:67]
	v_pk_add_f32 v[62:63], v[70:71], v[76:77]
	v_lshlrev_b32_e32 v69, 16, v59
	v_lshlrev_b32_e32 v68, 16, v58
	v_pk_add_f32 v[60:61], v[60:61], v[62:63]
	v_pk_add_f32 v[58:59], v[68:69], v[74:75]
	v_add_f32_e32 v12, 0, v60
	v_pk_add_f32 v[58:59], v[58:59], v[58:59] op_sel:[0,1] op_sel_hi:[1,0]
	v_add_f32_e32 v22, v12, v61
	v_mov_b32_e32 v59, v21
	v_pk_add_f32 v[58:59], v[22:23], v[58:59]
	v_pk_add_f32 v[60:61], v[26:27], v[24:25]
	v_and_b32_e32 v73, 0xffff0000, v57
	v_pk_add_f32 v[58:59], v[58:59], v[60:61]
	v_lshlrev_b32_e32 v61, 16, v57
	v_lshlrev_b32_e32 v60, 16, v56
	v_and_b32_e32 v72, 0xffff0000, v56
	v_pk_add_f32 v[56:57], v[60:61], v[72:73]
	v_pk_add_f32 v[58:59], v[58:59], v[58:59] op_sel:[0,1] op_sel_hi:[1,0]
	v_pk_add_f32 v[56:57], v[56:57], v[56:57] op_sel:[0,1] op_sel_hi:[1,0]
	v_add_f32_e32 v14, v16, v17
	v_add_f32_e32 v12, v18, v19
	v_mov_b32_e32 v59, v10
	v_mov_b32_e32 v57, v11
	v_pk_add_f32 v[56:57], v[58:59], v[56:57]
	v_pk_add_f32 v[58:59], v[14:15], v[12:13]
	s_nop 0
	v_pk_add_f32 v[56:57], v[56:57], v[58:59]
	s_nop 0
	v_add_f32_e32 v12, v56, v57
	s_nop 1
	v_mov_b32_dpp v14, v12 quad_perm:[1,0,3,2] row_mask:0xf bank_mask:0xf
	s_waitcnt lgkmcnt(0)
	v_add_f32_e32 v12, v12, v14
	s_nop 1
	v_mov_b32_dpp v14, v12 quad_perm:[2,3,0,1] row_mask:0xf bank_mask:0xf
	s_waitcnt lgkmcnt(0)
	v_add_f32_e32 v12, v12, v14
	s_nop 1
	v_mov_b32_dpp v14, v12 row_half_mirror row_mask:0xf bank_mask:0xf
	s_waitcnt lgkmcnt(0)
	v_add_f32_e32 v12, v12, v14
	s_nop 1
	v_mov_b32_dpp v14, v12 row_mirror row_mask:0xf bank_mask:0xf
	s_waitcnt lgkmcnt(0)
	v_add_f32_e32 v12, v12, v14
	v_mov_b32_e32 v14, v12
	v_mov_b32_e32 v139, v12
	s_nop 1
	v_permlane16_swap_b32_e32 v14, v139
	s_waitcnt lgkmcnt(0)
	s_nop 1
	v_add_f32_e32 v12, v14, v139
	v_mov_b32_e32 v14, v12
	v_mov_b32_e32 v139, v12
	s_nop 1
	v_permlane32_swap_b32_e32 v14, v139
	s_waitcnt lgkmcnt(0)
	s_nop 1
	v_add_f32_e32 v14, v14, v139
	v_fmac_f32_e32 v66, 0xba000000, v14
	v_fmac_f32_e32 v67, 0xba000000, v14
	v_fmac_f32_e32 v76, 0xba000000, v14
	v_fmac_f32_e32 v64, 0xba000000, v14
	v_fmac_f32_e32 v77, 0xba000000, v14
	v_fmac_f32_e32 v65, 0xba000000, v14
	v_pk_mul_f32 v[58:59], v[66:67], v[66:67]
	v_fmac_f32_e32 v70, 0xba000000, v14
	v_fmac_f32_e32 v71, 0xba000000, v14
	v_mov_b32_e32 v62, v65
	v_mov_b32_e32 v63, v67
	v_mov_b32_e32 v56, v64
	v_pk_fma_f32 v[64:65], v[64:65], v[64:65], v[58:59]
	v_mov_b32_e32 v67, v77
	v_mov_b32_e32 v59, v76
	v_pk_mul_f32 v[76:77], v[76:77], v[76:77]
	v_mov_b32_e32 v57, v66
	v_mov_b32_e32 v66, v71
	v_mov_b32_e32 v58, v70
	v_pk_fma_f32 v[70:71], v[70:71], v[70:71], v[76:77]
	v_fmac_f32_e32 v74, 0xba000000, v14
	v_fmac_f32_e32 v75, 0xba000000, v14
	v_fmac_f32_e32 v69, 0xba000000, v14
	v_pk_add_f32 v[64:65], v[64:65], v[70:71]
	v_fmac_f32_e32 v68, 0xba000000, v14
	v_mov_b32_e32 v70, v69
	v_mov_b32_e32 v71, v75
	v_mov_b32_e32 v69, v74
	v_pk_mul_f32 v[76:77], v[70:71], v[70:71]
	v_pk_mul_f32 v[74:75], v[68:69], v[68:69]
	v_fmac_f32_e32 v28, 0xba000000, v14
	v_pk_mov_b32 v[78:79], v[74:75], v[76:77] op_sel:[1,0]
	v_mov_b32_e32 v75, v77
	v_fmac_f32_e32 v29, 0xba000000, v14
	v_fmac_f32_e32 v30, 0xba000000, v14
	v_mul_f32_e32 v12, v28, v28
	v_pk_add_f32 v[74:75], v[78:79], v[74:75]
	v_fmac_f32_e32 v31, 0xba000000, v14
	v_pk_fma_f32 v[76:77], v[28:29], v[28:29], v[12:13] op_sel_hi:[1,1,0]
	v_mul_f32_e32 v12, v30, v30
	v_pk_add_f32 v[64:65], v[64:65], v[64:65] op_sel_hi:[0,1]
	v_pk_add_f32 v[74:75], v[74:75], v[74:75] op_sel_hi:[0,1]
	v_pk_fma_f32 v[78:79], v[30:31], v[30:31], v[12:13] op_sel_hi:[1,1,0]
	v_fmac_f32_e32 v25, 0xba000000, v14
	v_fmac_f32_e32 v27, 0xba000000, v14
	v_fmac_f32_e32 v21, 0xba000000, v14
	v_fmac_f32_e32 v23, 0xba000000, v14
	v_mul_f32_e32 v76, v23, v23
	v_mul_f32_e32 v78, v21, v21
	v_mul_f32_e32 v74, v27, v27
	v_mul_f32_e32 v64, v25, v25
	v_pk_add_f32 v[76:77], v[76:77], v[78:79]
	v_pk_add_f32 v[64:65], v[74:75], v[64:65]
	v_fmac_f32_e32 v72, 0xba000000, v14
	v_pk_add_f32 v[64:65], v[76:77], v[64:65]
	v_fmac_f32_e32 v73, 0xba000000, v14
	v_fmac_f32_e32 v61, 0xba000000, v14
	v_pk_add_f32 v[74:75], v[64:65], v[64:65] op_sel_hi:[0,1]
	v_fmac_f32_e32 v60, 0xba000000, v14
	v_mov_b32_e32 v64, v61
	v_mov_b32_e32 v65, v73
	v_mov_b32_e32 v61, v72
	v_pk_mul_f32 v[76:77], v[64:65], v[64:65]
	v_pk_mul_f32 v[72:73], v[60:61], v[60:61]
	v_fmac_f32_e32 v16, 0xba000000, v14
	v_pk_mov_b32 v[78:79], v[72:73], v[76:77] op_sel:[1,0]
	v_mov_b32_e32 v73, v77
	v_fmac_f32_e32 v17, 0xba000000, v14
	v_fmac_f32_e32 v18, 0xba000000, v14
	v_mul_f32_e32 v12, v16, v16
	v_pk_add_f32 v[72:73], v[78:79], v[72:73]
	v_fmac_f32_e32 v19, 0xba000000, v14
	v_pk_fma_f32 v[76:77], v[16:17], v[16:17], v[12:13] op_sel_hi:[1,1,0]
	v_mul_f32_e32 v12, v18, v18
	v_pk_add_f32 v[72:73], v[72:73], v[72:73] op_sel_hi:[0,1]
	v_pk_fma_f32 v[78:79], v[18:19], v[18:19], v[12:13] op_sel_hi:[1,1,0]
	v_fmac_f32_e32 v13, 0xba000000, v14
	v_fmac_f32_e32 v15, 0xba000000, v14
	v_fmac_f32_e32 v11, 0xba000000, v14
	v_fmac_f32_e32 v10, 0xba000000, v14
	v_mul_f32_e32 v72, v15, v15
	v_mul_f32_e32 v74, v13, v13
	v_mul_f32_e32 v76, v10, v10
	v_mul_f32_e32 v78, v11, v11
	v_pk_add_f32 v[72:73], v[72:73], v[74:75]
	v_lshlrev_b32_e32 v74, 2, v1
	v_pk_add_f32 v[76:77], v[76:77], v[78:79]
	v_ashrrev_i32_e32 v75, 31, v74
	v_pk_add_f32 v[72:73], v[76:77], v[72:73]
	v_lshlrev_b64 v[76:77], 2, v[74:75]
	v_lshl_add_u64 v[80:81], s[12:13], 0, v[76:77]
	v_lshl_add_u64 v[78:79], s[14:15], 0, v[76:77]
	s_nop 1
	v_mov_b64_e32 v[84:85], v[180:181]
	v_mov_b64_e32 v[86:87], v[182:183]
	s_nop 1
	v_mov_b64_e32 v[96:97], v[212:213]
	v_mov_b64_e32 v[98:99], v[214:215]
	v_add_f32_e32 v12, v72, v73
	s_nop 1
	v_mov_b32_dpp v14, v12 quad_perm:[1,0,3,2] row_mask:0xf bank_mask:0xf
	s_waitcnt lgkmcnt(0)
	v_add_f32_e32 v12, v12, v14
	s_nop 1
	v_mov_b32_dpp v14, v12 quad_perm:[2,3,0,1] row_mask:0xf bank_mask:0xf
	s_waitcnt lgkmcnt(0)
	v_add_f32_e32 v12, v12, v14
	s_nop 1
	v_mov_b32_dpp v14, v12 row_half_mirror row_mask:0xf bank_mask:0xf
	s_waitcnt lgkmcnt(0)
	v_add_f32_e32 v12, v12, v14
	s_nop 1
	v_mov_b32_dpp v14, v12 row_mirror row_mask:0xf bank_mask:0xf
	s_waitcnt lgkmcnt(0)
	v_add_f32_e32 v12, v12, v14
	v_mov_b32_e32 v14, v12
	v_mov_b32_e32 v139, v12
	s_nop 1
	v_permlane16_swap_b32_e32 v14, v139
	s_waitcnt lgkmcnt(0)
	s_nop 1
	v_add_f32_e32 v12, v14, v139
	v_mov_b32_e32 v14, v12
	v_mov_b32_e32 v139, v12
	s_nop 1
	v_permlane32_swap_b32_e32 v14, v139
	s_waitcnt lgkmcnt(0)
	s_nop 1
	v_add_f32_e32 v12, v14, v139
	v_fmamk_f32 v12, v12, 0x3a000000, v250
	v_cmp_gt_f32_e32 vcc, s96, v12
	v_mul_f32_e32 v14, 0x4f800000, v12
	s_nop 0
	v_cndmask_b32_e32 v12, v12, v14, vcc
	v_sqrt_f32_e32 v14, v12
	s_nop 0
	v_add_u32_e32 v20, -1, v14
	v_fma_f32 v22, -v20, v14, v12
	v_cmp_ge_f32_e64 s[10:11], 0, v22
	v_add_u32_e32 v22, 1, v14
	s_nop 0
	v_cndmask_b32_e64 v20, v14, v20, s[10:11]
	v_fma_f32 v14, -v22, v14, v12
	v_cmp_lt_f32_e64 s[10:11], 0, v14
	s_nop 1
	v_cndmask_b32_e64 v14, v20, v22, s[10:11]
	v_mul_f32_e32 v20, 0x37800000, v14
	v_cndmask_b32_e32 v14, v14, v20, vcc
	v_cmp_class_f32_e32 vcc, v12, v251
	s_nop 1
	v_cndmask_b32_e32 v12, v14, v12, vcc
	v_div_scale_f32 v14, s[8:9], v12, v12, 1.0
	v_rcp_f32_e32 v20, v14
	s_mov_b64 s[8:9], 0x25d1e000
	v_fma_f32 v22, -v14, v20, 1.0
	v_fmac_f32_e32 v20, v22, v20
	v_div_scale_f32 v22, vcc, 1.0, v12, 1.0
	v_mul_f32_e32 v24, v22, v20
	v_fma_f32 v26, -v14, v24, v22
	v_fmac_f32_e32 v24, v26, v20
	v_fma_f32 v14, -v14, v24, v22
	v_div_fmas_f32 v14, v14, v20, v24
	v_div_fixup_f32 v14, v14, v12, 1.0
	v_pk_mul_f32 v[56:57], v[56:57], v[14:15] op_sel_hi:[1,0]
	v_pk_mul_f32 v[58:59], v[58:59], v[14:15] op_sel_hi:[1,0]
	s_waitcnt vmcnt(0)
	v_pk_fma_f32 v[96:97], v[84:85], v[56:57], v[96:97]
	v_lshl_add_u64 v[56:57], s[40:41], 0, v[76:77]
	v_pk_fma_f32 v[98:99], v[86:87], v[58:59], v[98:99]
	v_lshl_add_u64 v[86:87], v[56:57], 0, s[8:9]
	s_mov_b32 s8, 0x25d1f000
	v_add_co_u32_e32 v72, vcc, s8, v56
	v_lshl_add_u64 v[84:85], s[20:21], 0, v[76:77]
	s_nop 0
	v_addc_co_u32_e32 v73, vcc, 0, v57, vcc
	ds_read_b128 v[56:59], v127
	v_lshl_add_u64 v[76:77], s[18:19], 0, v[76:77]
	ds_read_b128 v[100:103], v127 offset:8192
	s_mov_b64 s[8:9], 0xcc1b000
	global_store_dwordx4 v[72:73], v[96:99], off offset:-4096
	v_pk_mul_f32 v[66:67], v[66:67], v[14:15] op_sel_hi:[1,0]
	v_pk_mul_f32 v[62:63], v[62:63], v[14:15] op_sel_hi:[1,0]
	v_pk_mul_f32 v[70:71], v[70:71], v[14:15] op_sel_hi:[1,0]
	v_pk_mul_f32 v[68:69], v[68:69], v[14:15] op_sel_hi:[1,0]
	v_pk_mul_f32 v[30:31], v[30:31], v[14:15] op_sel_hi:[1,0]
	v_pk_mul_f32 v[28:29], v[28:29], v[14:15] op_sel_hi:[1,0]
	v_mov_b32_e32 v24, v27
	v_pk_mul_f32 v[24:25], v[24:25], v[14:15] op_sel_hi:[1,0]
	v_pk_mul_f32 v[64:65], v[64:65], v[14:15] op_sel_hi:[1,0]
	v_pk_mul_f32 v[60:61], v[60:61], v[14:15] op_sel_hi:[1,0]
	v_pk_mul_f32 v[18:19], v[18:19], v[14:15] op_sel_hi:[1,0]
	v_pk_mul_f32 v[16:17], v[16:17], v[14:15] op_sel_hi:[1,0]
	v_pk_mul_f32 v[10:11], v[10:11], v[14:15] op_sel_hi:[1,0]
	s_waitcnt lgkmcnt(0)
	v_pk_add_f32 v[58:59], v[58:59], 1.0 op_sel_hi:[1,0]
	v_pk_add_f32 v[88:89], v[56:57], 1.0 op_sel_hi:[1,0]
	s_nop 0
	v_pk_fma_f32 v[56:57], v[58:59], v[98:99], v[102:103]
	v_pk_fma_f32 v[58:59], v[88:89], v[96:97], v[100:101]
	v_lshl_add_u64 v[96:97], v[74:75], 1, s[16:17]
	s_nop 0
	s_nop 0
	s_nop 0
	s_nop 0
	s_nop 0
	v_cvt_pk_bf16_f32 v88, v58, v59
	s_nop 0
	s_nop 0
	s_nop 0
	s_nop 0
	s_nop 0
	v_lshl_add_u64 v[74:75], v[96:97], 0, s[8:9]
	v_add_co_u32_e32 v96, vcc, s61, v96
	v_cvt_pk_bf16_f32 v89, v56, v57
	s_nop 0
	v_addc_co_u32_e32 v97, vcc, 0, v97, vcc
	global_store_dwordx2 v[96:97], v[88:89], off
	s_nop 1
	v_mov_b64_e32 v[96:97], v[184:185]
	v_mov_b64_e32 v[98:99], v[186:187]
	s_nop 0
	s_nop 1
	v_mov_b64_e32 v[100:101], v[216:217]
	v_mov_b64_e32 v[102:103], v[218:219]
	s_waitcnt vmcnt(0)
	v_pk_fma_f32 v[96:97], v[96:97], v[62:63], v[100:101]
	v_pk_fma_f32 v[98:99], v[98:99], v[66:67], v[102:103]
	global_store_dwordx4 v[86:87], v[96:99], off offset:1024
	ds_read_b128 v[100:103], v127 offset:1024
	ds_read_b128 v[104:107], v127 offset:9216
	s_waitcnt lgkmcnt(0)
	v_pk_add_f32 v[66:67], v[100:101], 1.0 op_sel_hi:[1,0]
	s_nop 0
	v_pk_fma_f32 v[66:67], v[66:67], v[96:97], v[104:105]
	v_pk_add_f32 v[62:63], v[102:103], 1.0 op_sel_hi:[1,0]
	v_pk_fma_f32 v[62:63], v[62:63], v[98:99], v[106:107]
	v_cvt_pk_bf16_f32 v88, v66, v67
	v_cvt_pk_bf16_f32 v89, v62, v63
	global_store_dwordx2 v[74:75], v[88:89], off offset:512
	s_nop 1
	v_mov_b64_e32 v[96:97], v[188:189]
	v_mov_b64_e32 v[98:99], v[190:191]
	s_nop 1
	v_mov_b64_e32 v[100:101], v[220:221]
	v_mov_b64_e32 v[102:103], v[222:223]
	s_waitcnt vmcnt(0)
	v_pk_fma_f32 v[96:97], v[96:97], v[68:69], v[100:101]
	v_pk_fma_f32 v[98:99], v[98:99], v[70:71], v[102:103]
	global_store_dwordx4 v[86:87], v[96:99], off offset:2048
	ds_read_b128 v[68:71], v127 offset:2048
	ds_read_b128 v[100:103], v127 offset:10240
	s_waitcnt lgkmcnt(0)
	v_pk_add_f32 v[70:71], v[70:71], 1.0 op_sel_hi:[1,0]
	v_pk_add_f32 v[88:89], v[68:69], 1.0 op_sel_hi:[1,0]
	s_nop 0
	v_pk_fma_f32 v[68:69], v[70:71], v[98:99], v[102:103]
	v_pk_fma_f32 v[70:71], v[88:89], v[96:97], v[100:101]
	s_nop 0
	s_nop 0
	s_nop 0
	s_nop 0
	s_nop 0
	s_nop 0
	v_cvt_pk_bf16_f32 v88, v70, v71
	s_nop 0
	s_nop 0
	s_nop 0
	s_nop 0
	s_nop 0
	v_cvt_pk_bf16_f32 v89, v68, v69
	global_store_dwordx2 v[74:75], v[88:89], off offset:1024
	s_nop 1
	v_mov_b64_e32 v[96:97], v[192:193]
	v_mov_b64_e32 v[98:99], v[194:195]
	s_nop 1
	v_mov_b64_e32 v[100:101], v[236:237]
	v_mov_b64_e32 v[102:103], v[238:239]
	v_add_co_u32_e32 v80, vcc, s82, v80
	s_waitcnt vmcnt(0)
	v_pk_fma_f32 v[96:97], v[96:97], v[28:29], v[100:101]
	v_pk_fma_f32 v[98:99], v[98:99], v[30:31], v[102:103]
	global_store_dwordx4 v[86:87], v[96:99], off offset:3072
	ds_read_b128 v[28:31], v127 offset:3072
	s_nop 0
	ds_read_b128 v[86:89], v127 offset:11264
	v_addc_co_u32_e32 v81, vcc, 0, v81, vcc
	v_add_co_u32_e32 v78, vcc, s82, v78
	s_waitcnt lgkmcnt(0)
	v_pk_add_f32 v[30:31], v[30:31], 1.0 op_sel_hi:[1,0]
	v_pk_add_f32 v[100:101], v[28:29], 1.0 op_sel_hi:[1,0]
	s_nop 0
	v_pk_fma_f32 v[28:29], v[30:31], v[98:99], v[88:89]
	v_pk_fma_f32 v[30:31], v[100:101], v[96:97], v[86:87]
	v_addc_co_u32_e32 v79, vcc, 0, v79, vcc
	s_nop 0
	s_nop 0
	s_nop 0
	s_nop 0
	s_nop 0
	v_cvt_pk_bf16_f32 v86, v30, v31
	s_nop 0
	s_nop 0
	s_nop 0
	s_nop 0
	s_nop 0
	v_cvt_pk_bf16_f32 v87, v28, v29
	global_store_dwordx2 v[74:75], v[86:87], off offset:1536
	s_nop 1
	v_mov_b64_e32 v[86:87], v[196:197]
	v_mov_b64_e32 v[88:89], v[198:199]
	s_nop 1
	v_mov_b64_e32 v[96:97], v[240:241]
	v_mov_b64_e32 v[98:99], v[242:243]
	v_add_co_u32_e32 v84, vcc, s82, v84
	v_mov_b32_e32 v20, v23
	s_nop 0
	v_addc_co_u32_e32 v85, vcc, 0, v85, vcc
	v_pk_mul_f32 v[20:21], v[20:21], v[14:15] op_sel_hi:[1,0]
	v_add_co_u32_e32 v76, vcc, s82, v76
	s_waitcnt vmcnt(0)
	v_pk_fma_f32 v[22:23], v[20:21], v[86:87], v[96:97]
	v_pk_fma_f32 v[24:25], v[24:25], v[88:89], v[98:99]
	ds_read_b128 v[86:89], v127 offset:4096
	v_addc_co_u32_e32 v77, vcc, 0, v77, vcc
	ds_read_b128 v[96:99], v127 offset:12288
	s_waitcnt lgkmcnt(0)
	v_pk_add_f32 v[26:27], v[86:87], 1.0 op_sel_hi:[1,0]
	global_store_dwordx4 v[72:73], v[22:25], off
	v_pk_add_f32 v[20:21], v[88:89], 1.0 op_sel_hi:[1,0]
	s_nop 0
	v_pk_fma_f32 v[22:23], v[22:23], v[26:27], v[96:97]
	v_pk_fma_f32 v[20:21], v[24:25], v[20:21], v[98:99]
	v_cvt_pk_bf16_f32 v24, v22, v23
	v_cvt_pk_bf16_f32 v25, v20, v21
	global_store_dwordx2 v[74:75], v[24:25], off offset:2048
	s_nop 1
	v_mov_b64_e32 v[24:25], v[200:201]
	v_mov_b64_e32 v[26:27], v[202:203]
	s_nop 0
	s_nop 1
	v_mov_b64_e32 v[86:87], v[128:129]
	v_mov_b64_e32 v[88:89], v[130:131]
	s_waitcnt vmcnt(0)
	v_pk_fma_f32 v[86:87], v[60:61], v[24:25], v[86:87]
	v_pk_fma_f32 v[88:89], v[64:65], v[26:27], v[88:89]
	global_store_dwordx4 v[72:73], v[86:89], off offset:1024
	ds_read_b128 v[24:27], v127 offset:5120
	ds_read_b128 v[96:99], v127 offset:13312
	s_waitcnt lgkmcnt(0)
	v_pk_add_f32 v[26:27], v[26:27], 1.0 op_sel_hi:[1,0]
	v_pk_add_f32 v[60:61], v[24:25], 1.0 op_sel_hi:[1,0]
	s_nop 0
	v_pk_fma_f32 v[24:25], v[88:89], v[26:27], v[98:99]
	v_pk_fma_f32 v[26:27], v[86:87], v[60:61], v[96:97]
	v_cvt_pk_bf16_f32 v60, v26, v27
	v_cvt_pk_bf16_f32 v61, v24, v25
	global_store_dwordx2 v[74:75], v[60:61], off offset:2560
	s_nop 1
	v_mov_b64_e32 v[86:87], v[204:205]
	v_mov_b64_e32 v[88:89], v[206:207]
	s_nop 1
	v_mov_b64_e32 v[96:97], v[132:133]
	v_mov_b64_e32 v[98:99], v[134:135]
	s_waitcnt vmcnt(0)
	v_pk_fma_f32 v[86:87], v[16:17], v[86:87], v[96:97]
	v_pk_fma_f32 v[88:89], v[18:19], v[88:89], v[98:99]
	global_store_dwordx4 v[72:73], v[86:89], off offset:2048
	ds_read_b128 v[16:19], v127 offset:6144
	ds_read_b128 v[96:99], v127 offset:14336
	s_waitcnt lgkmcnt(0)
	v_pk_add_f32 v[18:19], v[18:19], 1.0 op_sel_hi:[1,0]
	v_pk_add_f32 v[60:61], v[16:17], 1.0 op_sel_hi:[1,0]
	s_nop 0
	v_pk_fma_f32 v[16:17], v[88:89], v[18:19], v[98:99]
	v_pk_fma_f32 v[18:19], v[86:87], v[60:61], v[96:97]
	v_cvt_pk_bf16_f32 v60, v18, v19
	v_cvt_pk_bf16_f32 v61, v16, v17
	global_store_dwordx2 v[74:75], v[60:61], off offset:3072
	s_nop 1
	v_mov_b64_e32 v[86:87], v[208:209]
	v_mov_b64_e32 v[88:89], v[210:211]
	s_nop 0
	s_nop 1
	v_mov_b64_e32 v[78:79], v[140:141]
	v_mov_b64_e32 v[80:81], v[142:143]
	v_mov_b32_e32 v12, v15
	v_pk_mul_f32 v[60:61], v[12:13], v[14:15] op_sel_hi:[1,0]
	s_waitcnt vmcnt(0)
	v_pk_fma_f32 v[12:13], v[10:11], v[86:87], v[78:79]
	v_pk_fma_f32 v[14:15], v[60:61], v[88:89], v[80:81]
	global_store_dwordx4 v[72:73], v[12:15], off offset:3072
	ds_read_b128 v[78:81], v127 offset:7168
	s_nop 0
	global_load_dwordx4 v[84:87], v[76:77], off offset:3072
	s_waitcnt vmcnt(0) lgkmcnt(0)
	v_pk_add_f32 v[60:61], v[78:79], 1.0 op_sel_hi:[1,0]
	v_pk_add_f32 v[10:11], v[80:81], 1.0 op_sel_hi:[1,0]
	s_nop 0
	v_pk_fma_f32 v[12:13], v[12:13], v[60:61], v[84:85]
	v_pk_fma_f32 v[10:11], v[14:15], v[10:11], v[86:87]
	v_cvt_pk_bf16_f32 v14, v12, v13
	s_nop 0
	s_nop 0
	s_nop 0
	s_nop 0
	s_nop 0
	v_cvt_pk_bf16_f32 v15, v10, v11
	global_store_dwordx2 v[74:75], v[14:15], off offset:3584
	s_nop 0
	v_lshl_add_u32 v103, v1, 4, 0
	ds_read_b128 v[72:75], v103
	v_add_u32_e32 v80, 0x18400, v103
	s_waitcnt lgkmcnt(0)
	v_pk_fma_f32 v[14:15], v[4:5], v[72:73], 0 op_sel_hi:[1,1,0]
	v_pk_fma_f32 v[60:61], v[58:59], v[72:73], 0 op_sel_hi:[1,1,0]
	v_pk_fma_f32 v[14:15], v[2:3], v[74:75], v[14:15]
	v_pk_fma_f32 v[60:61], v[56:57], v[74:75], v[60:61]
	ds_read_b128 v[72:75], v103 offset:1024
	s_waitcnt lgkmcnt(0)
	v_pk_fma_f32 v[14:15], v[8:9], v[72:73], v[14:15]
	v_pk_fma_f32 v[60:61], v[66:67], v[72:73], v[60:61]
	v_pk_fma_f32 v[14:15], v[6:7], v[74:75], v[14:15]
	v_pk_fma_f32 v[60:61], v[62:63], v[74:75], v[60:61]
	ds_read_b128 v[72:75], v103 offset:2048
	s_waitcnt lgkmcnt(0)
	v_pk_fma_f32 v[14:15], v[34:35], v[72:73], v[14:15]
	v_pk_fma_f32 v[60:61], v[70:71], v[72:73], v[60:61]
	v_pk_fma_f32 v[14:15], v[32:33], v[74:75], v[14:15]
	v_pk_fma_f32 v[60:61], v[68:69], v[74:75], v[60:61]
	ds_read_b128 v[72:75], v103 offset:3072
	s_waitcnt lgkmcnt(0)
	v_pk_fma_f32 v[14:15], v[38:39], v[72:73], v[14:15]
	v_pk_fma_f32 v[60:61], v[30:31], v[72:73], v[60:61]
	v_pk_fma_f32 v[14:15], v[36:37], v[74:75], v[14:15]
	v_pk_fma_f32 v[60:61], v[28:29], v[74:75], v[60:61]
	ds_read_b128 v[72:75], v103 offset:4096
	s_waitcnt lgkmcnt(0)
	v_pk_fma_f32 v[14:15], v[42:43], v[72:73], v[14:15]
	v_pk_fma_f32 v[60:61], v[22:23], v[72:73], v[60:61]
	v_pk_fma_f32 v[14:15], v[40:41], v[74:75], v[14:15]
	v_pk_fma_f32 v[60:61], v[20:21], v[74:75], v[60:61]
	ds_read_b128 v[72:75], v103 offset:5120
	s_waitcnt lgkmcnt(0)
	v_pk_fma_f32 v[14:15], v[46:47], v[72:73], v[14:15]
	v_pk_fma_f32 v[60:61], v[26:27], v[72:73], v[60:61]
	v_pk_fma_f32 v[14:15], v[44:45], v[74:75], v[14:15]
	v_pk_fma_f32 v[60:61], v[24:25], v[74:75], v[60:61]
	ds_read_b128 v[72:75], v103 offset:6144
	s_waitcnt lgkmcnt(0)
	v_pk_fma_f32 v[14:15], v[50:51], v[72:73], v[14:15]
	v_pk_fma_f32 v[60:61], v[18:19], v[72:73], v[60:61]
	v_pk_fma_f32 v[14:15], v[48:49], v[74:75], v[14:15]
	v_pk_fma_f32 v[60:61], v[16:17], v[74:75], v[60:61]
	ds_read_b128 v[72:75], v103 offset:7168
	s_waitcnt lgkmcnt(0)
	v_pk_fma_f32 v[14:15], v[54:55], v[72:73], v[14:15]
	v_pk_fma_f32 v[60:61], v[12:13], v[72:73], v[60:61]
	v_pk_fma_f32 v[14:15], v[52:53], v[74:75], v[14:15]
	v_pk_fma_f32 v[60:61], v[10:11], v[74:75], v[60:61]
	v_add_f32_e32 v81, v14, v15
	v_add_f32_e32 v14, v60, v61
	ds_read_b128 v[72:75], v103 offset:8192
	s_waitcnt lgkmcnt(0)
	v_pk_fma_f32 v[60:61], v[4:5], v[72:73], 0 op_sel_hi:[1,1,0]
	v_pk_fma_f32 v[64:65], v[58:59], v[72:73], 0 op_sel_hi:[1,1,0]
	v_pk_fma_f32 v[60:61], v[2:3], v[74:75], v[60:61]
	v_pk_fma_f32 v[64:65], v[56:57], v[74:75], v[64:65]
	ds_read_b128 v[72:75], v103 offset:9216
	s_waitcnt lgkmcnt(0)
	v_pk_fma_f32 v[60:61], v[8:9], v[72:73], v[60:61]
	v_pk_fma_f32 v[64:65], v[66:67], v[72:73], v[64:65]
	v_pk_fma_f32 v[60:61], v[6:7], v[74:75], v[60:61]
	v_pk_fma_f32 v[64:65], v[62:63], v[74:75], v[64:65]
	ds_read_b128 v[72:75], v103 offset:10240
	s_waitcnt lgkmcnt(0)
	v_pk_fma_f32 v[60:61], v[34:35], v[72:73], v[60:61]
	v_pk_fma_f32 v[64:65], v[70:71], v[72:73], v[64:65]
	v_pk_fma_f32 v[60:61], v[32:33], v[74:75], v[60:61]
	v_pk_fma_f32 v[64:65], v[68:69], v[74:75], v[64:65]
	ds_read_b128 v[72:75], v103 offset:11264
	s_waitcnt lgkmcnt(0)
	v_pk_fma_f32 v[60:61], v[38:39], v[72:73], v[60:61]
	v_pk_fma_f32 v[64:65], v[30:31], v[72:73], v[64:65]
	v_pk_fma_f32 v[60:61], v[36:37], v[74:75], v[60:61]
	v_pk_fma_f32 v[64:65], v[28:29], v[74:75], v[64:65]
	ds_read_b128 v[72:75], v103 offset:12288
	s_waitcnt lgkmcnt(0)
	v_pk_fma_f32 v[60:61], v[42:43], v[72:73], v[60:61]
	v_pk_fma_f32 v[64:65], v[22:23], v[72:73], v[64:65]
	v_pk_fma_f32 v[60:61], v[40:41], v[74:75], v[60:61]
	v_pk_fma_f32 v[64:65], v[20:21], v[74:75], v[64:65]
	ds_read_b128 v[72:75], v103 offset:13312
	s_waitcnt lgkmcnt(0)
	v_pk_fma_f32 v[60:61], v[46:47], v[72:73], v[60:61]
	v_pk_fma_f32 v[64:65], v[26:27], v[72:73], v[64:65]
	v_pk_fma_f32 v[60:61], v[44:45], v[74:75], v[60:61]
	v_pk_fma_f32 v[64:65], v[24:25], v[74:75], v[64:65]
	ds_read_b128 v[72:75], v103 offset:14336
	s_waitcnt lgkmcnt(0)
	v_pk_fma_f32 v[60:61], v[50:51], v[72:73], v[60:61]
	v_pk_fma_f32 v[64:65], v[18:19], v[72:73], v[64:65]
	v_pk_fma_f32 v[60:61], v[48:49], v[74:75], v[60:61]
	v_pk_fma_f32 v[64:65], v[16:17], v[74:75], v[64:65]
	ds_read_b128 v[72:75], v103 offset:15360
	s_waitcnt lgkmcnt(0)
	v_pk_fma_f32 v[60:61], v[54:55], v[72:73], v[60:61]
	v_pk_fma_f32 v[64:65], v[12:13], v[72:73], v[64:65]
	v_pk_fma_f32 v[60:61], v[52:53], v[74:75], v[60:61]
	v_pk_fma_f32 v[64:65], v[10:11], v[74:75], v[64:65]
	v_add_f32_e32 v82, v60, v61
	v_add_f32_e32 v15, v64, v65
	ds_read_b128 v[72:75], v103 offset:16384
	s_waitcnt lgkmcnt(0)
	v_pk_fma_f32 v[60:61], v[4:5], v[72:73], 0 op_sel_hi:[1,1,0]
	v_pk_fma_f32 v[64:65], v[58:59], v[72:73], 0 op_sel_hi:[1,1,0]
	v_pk_fma_f32 v[60:61], v[2:3], v[74:75], v[60:61]
	v_pk_fma_f32 v[64:65], v[56:57], v[74:75], v[64:65]
	ds_read_b128 v[72:75], v103 offset:17408
	s_waitcnt lgkmcnt(0)
	v_pk_fma_f32 v[60:61], v[8:9], v[72:73], v[60:61]
	v_pk_fma_f32 v[64:65], v[66:67], v[72:73], v[64:65]
	v_pk_fma_f32 v[60:61], v[6:7], v[74:75], v[60:61]
	v_pk_fma_f32 v[64:65], v[62:63], v[74:75], v[64:65]
	ds_read_b128 v[72:75], v103 offset:18432
	s_waitcnt lgkmcnt(0)
	v_pk_fma_f32 v[60:61], v[34:35], v[72:73], v[60:61]
	v_pk_fma_f32 v[64:65], v[70:71], v[72:73], v[64:65]
	v_pk_fma_f32 v[60:61], v[32:33], v[74:75], v[60:61]
	v_pk_fma_f32 v[64:65], v[68:69], v[74:75], v[64:65]
	ds_read_b128 v[72:75], v103 offset:19456
	s_waitcnt lgkmcnt(0)
	v_pk_fma_f32 v[60:61], v[38:39], v[72:73], v[60:61]
	v_pk_fma_f32 v[64:65], v[30:31], v[72:73], v[64:65]
	v_pk_fma_f32 v[60:61], v[36:37], v[74:75], v[60:61]
	v_pk_fma_f32 v[64:65], v[28:29], v[74:75], v[64:65]
	ds_read_b128 v[72:75], v103 offset:20480
	s_waitcnt lgkmcnt(0)
	v_pk_fma_f32 v[60:61], v[42:43], v[72:73], v[60:61]
	v_pk_fma_f32 v[64:65], v[22:23], v[72:73], v[64:65]
	v_pk_fma_f32 v[60:61], v[40:41], v[74:75], v[60:61]
	v_pk_fma_f32 v[64:65], v[20:21], v[74:75], v[64:65]
	ds_read_b128 v[72:75], v103 offset:21504
	s_waitcnt lgkmcnt(0)
	v_pk_fma_f32 v[60:61], v[46:47], v[72:73], v[60:61]
	v_pk_fma_f32 v[64:65], v[26:27], v[72:73], v[64:65]
	v_pk_fma_f32 v[60:61], v[44:45], v[74:75], v[60:61]
	v_pk_fma_f32 v[64:65], v[24:25], v[74:75], v[64:65]
	ds_read_b128 v[72:75], v103 offset:22528
	s_waitcnt lgkmcnt(0)
	v_pk_fma_f32 v[60:61], v[50:51], v[72:73], v[60:61]
	v_pk_fma_f32 v[64:65], v[18:19], v[72:73], v[64:65]
	v_pk_fma_f32 v[60:61], v[48:49], v[74:75], v[60:61]
	v_pk_fma_f32 v[64:65], v[16:17], v[74:75], v[64:65]
	ds_read_b128 v[72:75], v103 offset:23552
	s_waitcnt lgkmcnt(0)
	v_pk_fma_f32 v[60:61], v[54:55], v[72:73], v[60:61]
	v_pk_fma_f32 v[64:65], v[12:13], v[72:73], v[64:65]
	v_pk_fma_f32 v[60:61], v[52:53], v[74:75], v[60:61]
	v_pk_fma_f32 v[64:65], v[10:11], v[74:75], v[64:65]
	v_add_f32_e32 v84, v60, v61
	v_add_f32_e32 v60, v64, v65
	ds_read_b128 v[72:75], v103 offset:24576
	s_waitcnt lgkmcnt(0)
	v_pk_fma_f32 v[64:65], v[4:5], v[72:73], 0 op_sel_hi:[1,1,0]
	v_pk_fma_f32 v[72:73], v[58:59], v[72:73], 0 op_sel_hi:[1,1,0]
	v_pk_fma_f32 v[64:65], v[2:3], v[74:75], v[64:65]
	v_pk_fma_f32 v[76:77], v[56:57], v[74:75], v[72:73]
	ds_read_b128 v[72:75], v103 offset:25600
	s_waitcnt lgkmcnt(0)
	v_pk_fma_f32 v[64:65], v[8:9], v[72:73], v[64:65]
	v_pk_fma_f32 v[72:73], v[66:67], v[72:73], v[76:77]
	v_pk_fma_f32 v[64:65], v[6:7], v[74:75], v[64:65]
	v_pk_fma_f32 v[76:77], v[62:63], v[74:75], v[72:73]
	ds_read_b128 v[72:75], v103 offset:26624
	s_waitcnt lgkmcnt(0)
	v_pk_fma_f32 v[64:65], v[34:35], v[72:73], v[64:65]
	v_pk_fma_f32 v[72:73], v[70:71], v[72:73], v[76:77]
	v_pk_fma_f32 v[64:65], v[32:33], v[74:75], v[64:65]
	v_pk_fma_f32 v[76:77], v[68:69], v[74:75], v[72:73]
	ds_read_b128 v[72:75], v103 offset:27648
	s_waitcnt lgkmcnt(0)
	v_pk_fma_f32 v[64:65], v[38:39], v[72:73], v[64:65]
	v_pk_fma_f32 v[72:73], v[30:31], v[72:73], v[76:77]
	v_pk_fma_f32 v[64:65], v[36:37], v[74:75], v[64:65]
	v_pk_fma_f32 v[76:77], v[28:29], v[74:75], v[72:73]
	ds_read_b128 v[72:75], v103 offset:28672
	s_waitcnt lgkmcnt(0)
	v_pk_fma_f32 v[64:65], v[42:43], v[72:73], v[64:65]
	v_pk_fma_f32 v[72:73], v[22:23], v[72:73], v[76:77]
	v_pk_fma_f32 v[64:65], v[40:41], v[74:75], v[64:65]
	v_pk_fma_f32 v[76:77], v[20:21], v[74:75], v[72:73]
	ds_read_b128 v[72:75], v103 offset:29696
	s_waitcnt lgkmcnt(0)
	v_pk_fma_f32 v[64:65], v[46:47], v[72:73], v[64:65]
	v_pk_fma_f32 v[72:73], v[26:27], v[72:73], v[76:77]
	v_pk_fma_f32 v[64:65], v[44:45], v[74:75], v[64:65]
	v_pk_fma_f32 v[76:77], v[24:25], v[74:75], v[72:73]
	ds_read_b128 v[72:75], v103 offset:30720
	s_waitcnt lgkmcnt(0)
	v_pk_fma_f32 v[64:65], v[50:51], v[72:73], v[64:65]
	v_pk_fma_f32 v[72:73], v[18:19], v[72:73], v[76:77]
	v_pk_fma_f32 v[64:65], v[48:49], v[74:75], v[64:65]
	v_pk_fma_f32 v[76:77], v[16:17], v[74:75], v[72:73]
	ds_read_b128 v[72:75], v103 offset:31744
	s_waitcnt lgkmcnt(0)
	v_pk_fma_f32 v[64:65], v[54:55], v[72:73], v[64:65]
	v_pk_fma_f32 v[72:73], v[12:13], v[72:73], v[76:77]
	v_pk_fma_f32 v[64:65], v[52:53], v[74:75], v[64:65]
	v_pk_fma_f32 v[72:73], v[10:11], v[74:75], v[72:73]
	v_add_f32_e32 v85, v64, v65
	v_add_f32_e32 v61, v72, v73
	ds_read_b128 v[72:75], v103 offset:32768
	s_waitcnt lgkmcnt(0)
	v_pk_fma_f32 v[64:65], v[4:5], v[72:73], 0 op_sel_hi:[1,1,0]
	v_pk_fma_f32 v[72:73], v[58:59], v[72:73], 0 op_sel_hi:[1,1,0]
	v_pk_fma_f32 v[64:65], v[2:3], v[74:75], v[64:65]
	v_pk_fma_f32 v[76:77], v[56:57], v[74:75], v[72:73]
	ds_read_b128 v[72:75], v103 offset:33792
	s_waitcnt lgkmcnt(0)
	v_pk_fma_f32 v[64:65], v[8:9], v[72:73], v[64:65]
	v_pk_fma_f32 v[72:73], v[66:67], v[72:73], v[76:77]
	v_pk_fma_f32 v[64:65], v[6:7], v[74:75], v[64:65]
	v_pk_fma_f32 v[76:77], v[62:63], v[74:75], v[72:73]
	ds_read_b128 v[72:75], v103 offset:34816
	s_waitcnt lgkmcnt(0)
	v_pk_fma_f32 v[64:65], v[34:35], v[72:73], v[64:65]
	v_pk_fma_f32 v[72:73], v[70:71], v[72:73], v[76:77]
	v_pk_fma_f32 v[64:65], v[32:33], v[74:75], v[64:65]
	v_pk_fma_f32 v[76:77], v[68:69], v[74:75], v[72:73]
	ds_read_b128 v[72:75], v103 offset:35840
	s_waitcnt lgkmcnt(0)
	v_pk_fma_f32 v[64:65], v[38:39], v[72:73], v[64:65]
	v_pk_fma_f32 v[72:73], v[30:31], v[72:73], v[76:77]
	v_pk_fma_f32 v[64:65], v[36:37], v[74:75], v[64:65]
	v_pk_fma_f32 v[76:77], v[28:29], v[74:75], v[72:73]
	ds_read_b128 v[72:75], v103 offset:36864
	s_waitcnt lgkmcnt(0)
	v_pk_fma_f32 v[64:65], v[42:43], v[72:73], v[64:65]
	v_pk_fma_f32 v[72:73], v[22:23], v[72:73], v[76:77]
	v_pk_fma_f32 v[64:65], v[40:41], v[74:75], v[64:65]
	v_pk_fma_f32 v[76:77], v[20:21], v[74:75], v[72:73]
	ds_read_b128 v[72:75], v103 offset:37888
	s_waitcnt lgkmcnt(0)
	v_pk_fma_f32 v[64:65], v[46:47], v[72:73], v[64:65]
	v_pk_fma_f32 v[72:73], v[26:27], v[72:73], v[76:77]
	v_pk_fma_f32 v[64:65], v[44:45], v[74:75], v[64:65]
	v_pk_fma_f32 v[76:77], v[24:25], v[74:75], v[72:73]
	ds_read_b128 v[72:75], v103 offset:38912
	s_waitcnt lgkmcnt(0)
	v_pk_fma_f32 v[64:65], v[50:51], v[72:73], v[64:65]
	v_pk_fma_f32 v[72:73], v[18:19], v[72:73], v[76:77]
	v_pk_fma_f32 v[64:65], v[48:49], v[74:75], v[64:65]
	v_pk_fma_f32 v[76:77], v[16:17], v[74:75], v[72:73]
	ds_read_b128 v[72:75], v103 offset:39936
	s_waitcnt lgkmcnt(0)
	v_pk_fma_f32 v[64:65], v[54:55], v[72:73], v[64:65]
	v_pk_fma_f32 v[72:73], v[12:13], v[72:73], v[76:77]
	v_pk_fma_f32 v[64:65], v[52:53], v[74:75], v[64:65]
	v_pk_fma_f32 v[72:73], v[10:11], v[74:75], v[72:73]
	v_add_f32_e32 v86, v64, v65
	v_add_f32_e32 v64, v72, v73
	ds_read_b128 v[72:75], v103 offset:40960
	s_waitcnt lgkmcnt(0)
	v_pk_fma_f32 v[76:77], v[4:5], v[72:73], 0 op_sel_hi:[1,1,0]
	v_pk_fma_f32 v[72:73], v[58:59], v[72:73], 0 op_sel_hi:[1,1,0]
	v_pk_fma_f32 v[76:77], v[2:3], v[74:75], v[76:77]
	v_pk_fma_f32 v[78:79], v[56:57], v[74:75], v[72:73]
	ds_read_b128 v[72:75], v103 offset:41984
	s_waitcnt lgkmcnt(0)
	v_pk_fma_f32 v[76:77], v[8:9], v[72:73], v[76:77]
	v_pk_fma_f32 v[72:73], v[66:67], v[72:73], v[78:79]
	v_pk_fma_f32 v[76:77], v[6:7], v[74:75], v[76:77]
	v_pk_fma_f32 v[78:79], v[62:63], v[74:75], v[72:73]
	ds_read_b128 v[72:75], v103 offset:43008
	s_waitcnt lgkmcnt(0)
	v_pk_fma_f32 v[76:77], v[34:35], v[72:73], v[76:77]
	v_pk_fma_f32 v[72:73], v[70:71], v[72:73], v[78:79]
	v_pk_fma_f32 v[76:77], v[32:33], v[74:75], v[76:77]
	v_pk_fma_f32 v[78:79], v[68:69], v[74:75], v[72:73]
	ds_read_b128 v[72:75], v103 offset:44032
	s_waitcnt lgkmcnt(0)
	v_pk_fma_f32 v[76:77], v[38:39], v[72:73], v[76:77]
	v_pk_fma_f32 v[72:73], v[30:31], v[72:73], v[78:79]
	v_pk_fma_f32 v[76:77], v[36:37], v[74:75], v[76:77]
	v_pk_fma_f32 v[78:79], v[28:29], v[74:75], v[72:73]
	ds_read_b128 v[72:75], v103 offset:45056
	s_waitcnt lgkmcnt(0)
	v_pk_fma_f32 v[76:77], v[42:43], v[72:73], v[76:77]
	v_pk_fma_f32 v[72:73], v[22:23], v[72:73], v[78:79]
	v_pk_fma_f32 v[76:77], v[40:41], v[74:75], v[76:77]
	v_pk_fma_f32 v[78:79], v[20:21], v[74:75], v[72:73]
	ds_read_b128 v[72:75], v103 offset:46080
	s_waitcnt lgkmcnt(0)
	v_pk_fma_f32 v[76:77], v[46:47], v[72:73], v[76:77]
	v_pk_fma_f32 v[72:73], v[26:27], v[72:73], v[78:79]
	v_pk_fma_f32 v[76:77], v[44:45], v[74:75], v[76:77]
	v_pk_fma_f32 v[78:79], v[24:25], v[74:75], v[72:73]
	ds_read_b128 v[72:75], v103 offset:47104
	s_waitcnt lgkmcnt(0)
	v_pk_fma_f32 v[76:77], v[50:51], v[72:73], v[76:77]
	v_pk_fma_f32 v[72:73], v[18:19], v[72:73], v[78:79]
	v_pk_fma_f32 v[76:77], v[48:49], v[74:75], v[76:77]
	v_pk_fma_f32 v[78:79], v[16:17], v[74:75], v[72:73]
	ds_read_b128 v[72:75], v103 offset:48128
	s_waitcnt lgkmcnt(0)
	v_pk_fma_f32 v[76:77], v[54:55], v[72:73], v[76:77]
	v_pk_fma_f32 v[72:73], v[12:13], v[72:73], v[78:79]
	v_pk_fma_f32 v[76:77], v[52:53], v[74:75], v[76:77]
	v_pk_fma_f32 v[72:73], v[10:11], v[74:75], v[72:73]
	v_add_f32_e32 v87, v76, v77
	v_add_f32_e32 v65, v72, v73
	ds_read_b128 v[72:75], v103 offset:49152
	s_waitcnt lgkmcnt(0)
	v_pk_fma_f32 v[76:77], v[4:5], v[72:73], 0 op_sel_hi:[1,1,0]
	v_pk_fma_f32 v[72:73], v[58:59], v[72:73], 0 op_sel_hi:[1,1,0]
	v_pk_fma_f32 v[76:77], v[2:3], v[74:75], v[76:77]
	v_pk_fma_f32 v[78:79], v[56:57], v[74:75], v[72:73]
	ds_read_b128 v[72:75], v103 offset:50176
	s_waitcnt lgkmcnt(0)
	v_pk_fma_f32 v[76:77], v[8:9], v[72:73], v[76:77]
	v_pk_fma_f32 v[72:73], v[66:67], v[72:73], v[78:79]
	v_pk_fma_f32 v[76:77], v[6:7], v[74:75], v[76:77]
	v_pk_fma_f32 v[78:79], v[62:63], v[74:75], v[72:73]
	ds_read_b128 v[72:75], v103 offset:51200
	s_waitcnt lgkmcnt(0)
	v_pk_fma_f32 v[76:77], v[34:35], v[72:73], v[76:77]
	v_pk_fma_f32 v[72:73], v[70:71], v[72:73], v[78:79]
	v_pk_fma_f32 v[76:77], v[32:33], v[74:75], v[76:77]
	v_pk_fma_f32 v[78:79], v[68:69], v[74:75], v[72:73]
	ds_read_b128 v[72:75], v103 offset:52224
	s_waitcnt lgkmcnt(0)
	v_pk_fma_f32 v[76:77], v[38:39], v[72:73], v[76:77]
	v_pk_fma_f32 v[72:73], v[30:31], v[72:73], v[78:79]
	v_pk_fma_f32 v[76:77], v[36:37], v[74:75], v[76:77]
	v_pk_fma_f32 v[78:79], v[28:29], v[74:75], v[72:73]
	ds_read_b128 v[72:75], v103 offset:53248
	s_waitcnt lgkmcnt(0)
	v_pk_fma_f32 v[76:77], v[42:43], v[72:73], v[76:77]
	v_pk_fma_f32 v[72:73], v[22:23], v[72:73], v[78:79]
	v_pk_fma_f32 v[76:77], v[40:41], v[74:75], v[76:77]
	v_pk_fma_f32 v[78:79], v[20:21], v[74:75], v[72:73]
	ds_read_b128 v[72:75], v103 offset:54272
	s_waitcnt lgkmcnt(0)
	v_pk_fma_f32 v[76:77], v[46:47], v[72:73], v[76:77]
	v_pk_fma_f32 v[72:73], v[26:27], v[72:73], v[78:79]
	v_pk_fma_f32 v[76:77], v[44:45], v[74:75], v[76:77]
	v_pk_fma_f32 v[78:79], v[24:25], v[74:75], v[72:73]
	ds_read_b128 v[72:75], v103 offset:55296
	s_waitcnt lgkmcnt(0)
	v_pk_fma_f32 v[76:77], v[50:51], v[72:73], v[76:77]
	v_pk_fma_f32 v[72:73], v[18:19], v[72:73], v[78:79]
	v_pk_fma_f32 v[76:77], v[48:49], v[74:75], v[76:77]
	v_pk_fma_f32 v[78:79], v[16:17], v[74:75], v[72:73]
	ds_read_b128 v[72:75], v103 offset:56320
	s_waitcnt lgkmcnt(0)
	v_pk_fma_f32 v[76:77], v[54:55], v[72:73], v[76:77]
	v_pk_fma_f32 v[72:73], v[12:13], v[72:73], v[78:79]
	v_pk_fma_f32 v[76:77], v[52:53], v[74:75], v[76:77]
	v_pk_fma_f32 v[72:73], v[10:11], v[74:75], v[72:73]
	v_add_f32_e32 v88, v76, v77
	v_add_f32_e32 v72, v72, v73
	ds_read_b128 v[74:77], v103 offset:57344
	s_waitcnt lgkmcnt(0)
	v_pk_fma_f32 v[78:79], v[4:5], v[74:75], 0 op_sel_hi:[1,1,0]
	v_pk_fma_f32 v[74:75], v[58:59], v[74:75], 0 op_sel_hi:[1,1,0]
	v_pk_fma_f32 v[78:79], v[2:3], v[76:77], v[78:79]
	v_pk_fma_f32 v[96:97], v[56:57], v[76:77], v[74:75]
	ds_read_b128 v[74:77], v103 offset:58368
	s_waitcnt lgkmcnt(0)
	v_pk_fma_f32 v[78:79], v[8:9], v[74:75], v[78:79]
	v_pk_fma_f32 v[74:75], v[66:67], v[74:75], v[96:97]
	v_pk_fma_f32 v[78:79], v[6:7], v[76:77], v[78:79]
	v_pk_fma_f32 v[96:97], v[62:63], v[76:77], v[74:75]
	ds_read_b128 v[74:77], v103 offset:59392
	s_waitcnt lgkmcnt(0)
	v_pk_fma_f32 v[78:79], v[34:35], v[74:75], v[78:79]
	v_pk_fma_f32 v[74:75], v[70:71], v[74:75], v[96:97]
	v_pk_fma_f32 v[78:79], v[32:33], v[76:77], v[78:79]
	v_pk_fma_f32 v[96:97], v[68:69], v[76:77], v[74:75]
	ds_read_b128 v[74:77], v103 offset:60416
	s_waitcnt lgkmcnt(0)
	v_pk_fma_f32 v[78:79], v[38:39], v[74:75], v[78:79]
	v_pk_fma_f32 v[74:75], v[30:31], v[74:75], v[96:97]
	v_pk_fma_f32 v[78:79], v[36:37], v[76:77], v[78:79]
	v_pk_fma_f32 v[96:97], v[28:29], v[76:77], v[74:75]
	ds_read_b128 v[74:77], v103 offset:61440
	s_waitcnt lgkmcnt(0)
	v_pk_fma_f32 v[78:79], v[42:43], v[74:75], v[78:79]
	v_pk_fma_f32 v[74:75], v[22:23], v[74:75], v[96:97]
	v_pk_fma_f32 v[78:79], v[40:41], v[76:77], v[78:79]
	v_pk_fma_f32 v[96:97], v[20:21], v[76:77], v[74:75]
	ds_read_b128 v[74:77], v103 offset:62464
	s_waitcnt lgkmcnt(0)
	v_pk_fma_f32 v[78:79], v[46:47], v[74:75], v[78:79]
	v_pk_fma_f32 v[74:75], v[26:27], v[74:75], v[96:97]
	v_pk_fma_f32 v[78:79], v[44:45], v[76:77], v[78:79]
	v_pk_fma_f32 v[96:97], v[24:25], v[76:77], v[74:75]
	ds_read_b128 v[74:77], v103 offset:63488
	s_waitcnt lgkmcnt(0)
	v_pk_fma_f32 v[78:79], v[50:51], v[74:75], v[78:79]
	v_pk_fma_f32 v[74:75], v[18:19], v[74:75], v[96:97]
	v_pk_fma_f32 v[78:79], v[48:49], v[76:77], v[78:79]
	v_pk_fma_f32 v[96:97], v[16:17], v[76:77], v[74:75]
	ds_read_b128 v[74:77], v103 offset:64512
	s_waitcnt lgkmcnt(0)
	v_pk_fma_f32 v[78:79], v[54:55], v[74:75], v[78:79]
	v_pk_fma_f32 v[74:75], v[12:13], v[74:75], v[96:97]
	v_pk_fma_f32 v[78:79], v[52:53], v[76:77], v[78:79]
	v_pk_fma_f32 v[74:75], v[10:11], v[76:77], v[74:75]
	v_add_f32_e32 v89, v78, v79
	v_add_f32_e32 v73, v74, v75
	v_add_u32_e32 v74, 0x10000, v103
	ds_read_b128 v[74:77], v74
	s_waitcnt lgkmcnt(0)
	v_pk_fma_f32 v[78:79], v[4:5], v[74:75], 0 op_sel_hi:[1,1,0]
	v_pk_fma_f32 v[74:75], v[58:59], v[74:75], 0 op_sel_hi:[1,1,0]
	v_pk_fma_f32 v[78:79], v[2:3], v[76:77], v[78:79]
	v_pk_fma_f32 v[96:97], v[56:57], v[76:77], v[74:75]
	v_add_u32_e32 v74, 0x10400, v103
	ds_read_b128 v[74:77], v74
	s_waitcnt lgkmcnt(0)
	v_pk_fma_f32 v[78:79], v[8:9], v[74:75], v[78:79]
	v_pk_fma_f32 v[74:75], v[66:67], v[74:75], v[96:97]
	v_pk_fma_f32 v[78:79], v[6:7], v[76:77], v[78:79]
	v_pk_fma_f32 v[96:97], v[62:63], v[76:77], v[74:75]
	v_add_u32_e32 v74, 0x10800, v103
	ds_read_b128 v[74:77], v74
	s_waitcnt lgkmcnt(0)
	v_pk_fma_f32 v[78:79], v[34:35], v[74:75], v[78:79]
	v_pk_fma_f32 v[74:75], v[70:71], v[74:75], v[96:97]
	v_pk_fma_f32 v[78:79], v[32:33], v[76:77], v[78:79]
	v_pk_fma_f32 v[96:97], v[68:69], v[76:77], v[74:75]
	v_add_u32_e32 v74, 0x10c00, v103
	ds_read_b128 v[74:77], v74
	s_waitcnt lgkmcnt(0)
	v_pk_fma_f32 v[78:79], v[38:39], v[74:75], v[78:79]
	v_pk_fma_f32 v[74:75], v[30:31], v[74:75], v[96:97]
	v_pk_fma_f32 v[78:79], v[36:37], v[76:77], v[78:79]
	v_pk_fma_f32 v[96:97], v[28:29], v[76:77], v[74:75]
	v_add_u32_e32 v74, 0x11000, v103
	ds_read_b128 v[74:77], v74
	s_waitcnt lgkmcnt(0)
	v_pk_fma_f32 v[78:79], v[42:43], v[74:75], v[78:79]
	v_pk_fma_f32 v[74:75], v[22:23], v[74:75], v[96:97]
	v_pk_fma_f32 v[78:79], v[40:41], v[76:77], v[78:79]
	v_pk_fma_f32 v[96:97], v[20:21], v[76:77], v[74:75]
	v_add_u32_e32 v74, 0x11400, v103
	ds_read_b128 v[74:77], v74
	s_waitcnt lgkmcnt(0)
	v_pk_fma_f32 v[78:79], v[46:47], v[74:75], v[78:79]
	v_pk_fma_f32 v[74:75], v[26:27], v[74:75], v[96:97]
	v_pk_fma_f32 v[78:79], v[44:45], v[76:77], v[78:79]
	v_pk_fma_f32 v[96:97], v[24:25], v[76:77], v[74:75]
	v_add_u32_e32 v74, 0x11800, v103
	ds_read_b128 v[74:77], v74
	s_waitcnt lgkmcnt(0)
	v_pk_fma_f32 v[78:79], v[50:51], v[74:75], v[78:79]
	v_pk_fma_f32 v[74:75], v[18:19], v[74:75], v[96:97]
	v_pk_fma_f32 v[78:79], v[48:49], v[76:77], v[78:79]
	v_pk_fma_f32 v[96:97], v[16:17], v[76:77], v[74:75]
	v_add_u32_e32 v74, 0x11c00, v103
	ds_read_b128 v[74:77], v74
	s_waitcnt lgkmcnt(0)
	v_pk_fma_f32 v[78:79], v[54:55], v[74:75], v[78:79]
	v_pk_fma_f32 v[74:75], v[12:13], v[74:75], v[96:97]
	v_pk_fma_f32 v[78:79], v[52:53], v[76:77], v[78:79]
	v_pk_fma_f32 v[74:75], v[10:11], v[76:77], v[74:75]
	v_add_f32_e32 v96, v78, v79
	v_add_f32_e32 v74, v74, v75
	v_add_u32_e32 v75, 0x12000, v103
	ds_read_b128 v[76:79], v75
	v_add_u32_e32 v75, 0x12400, v103
	s_waitcnt lgkmcnt(0)
	v_pk_fma_f32 v[98:99], v[4:5], v[76:77], 0 op_sel_hi:[1,1,0]
	v_pk_fma_f32 v[76:77], v[58:59], v[76:77], 0 op_sel_hi:[1,1,0]
	v_pk_fma_f32 v[98:99], v[2:3], v[78:79], v[98:99]
	v_pk_fma_f32 v[100:101], v[56:57], v[78:79], v[76:77]
	ds_read_b128 v[76:79], v75
	v_add_u32_e32 v75, 0x12800, v103
	s_waitcnt lgkmcnt(0)
	v_pk_fma_f32 v[98:99], v[8:9], v[76:77], v[98:99]
	v_pk_fma_f32 v[76:77], v[66:67], v[76:77], v[100:101]
	v_pk_fma_f32 v[98:99], v[6:7], v[78:79], v[98:99]
	v_pk_fma_f32 v[100:101], v[62:63], v[78:79], v[76:77]
	ds_read_b128 v[76:79], v75
	v_add_u32_e32 v75, 0x12c00, v103
	s_waitcnt lgkmcnt(0)
	v_pk_fma_f32 v[98:99], v[34:35], v[76:77], v[98:99]
	v_pk_fma_f32 v[76:77], v[70:71], v[76:77], v[100:101]
	v_pk_fma_f32 v[98:99], v[32:33], v[78:79], v[98:99]
	v_pk_fma_f32 v[100:101], v[68:69], v[78:79], v[76:77]
	ds_read_b128 v[76:79], v75
	v_add_u32_e32 v75, 0x13000, v103
	s_waitcnt lgkmcnt(0)
	v_pk_fma_f32 v[98:99], v[38:39], v[76:77], v[98:99]
	v_pk_fma_f32 v[76:77], v[30:31], v[76:77], v[100:101]
	v_pk_fma_f32 v[98:99], v[36:37], v[78:79], v[98:99]
	v_pk_fma_f32 v[100:101], v[28:29], v[78:79], v[76:77]
	ds_read_b128 v[76:79], v75
	v_add_u32_e32 v75, 0x13400, v103
	s_waitcnt lgkmcnt(0)
	v_pk_fma_f32 v[98:99], v[42:43], v[76:77], v[98:99]
	v_pk_fma_f32 v[76:77], v[22:23], v[76:77], v[100:101]
	v_pk_fma_f32 v[98:99], v[40:41], v[78:79], v[98:99]
	v_pk_fma_f32 v[100:101], v[20:21], v[78:79], v[76:77]
	ds_read_b128 v[76:79], v75
	v_add_u32_e32 v75, 0x13800, v103
	s_waitcnt lgkmcnt(0)
	v_pk_fma_f32 v[98:99], v[46:47], v[76:77], v[98:99]
	v_pk_fma_f32 v[76:77], v[26:27], v[76:77], v[100:101]
	v_pk_fma_f32 v[98:99], v[44:45], v[78:79], v[98:99]
	v_pk_fma_f32 v[100:101], v[24:25], v[78:79], v[76:77]
	ds_read_b128 v[76:79], v75
	v_add_u32_e32 v75, 0x13c00, v103
	s_waitcnt lgkmcnt(0)
	v_pk_fma_f32 v[98:99], v[50:51], v[76:77], v[98:99]
	v_pk_fma_f32 v[76:77], v[18:19], v[76:77], v[100:101]
	v_pk_fma_f32 v[98:99], v[48:49], v[78:79], v[98:99]
	v_pk_fma_f32 v[100:101], v[16:17], v[78:79], v[76:77]
	ds_read_b128 v[76:79], v75
	s_waitcnt lgkmcnt(0)
	v_pk_fma_f32 v[98:99], v[54:55], v[76:77], v[98:99]
	v_pk_fma_f32 v[76:77], v[12:13], v[76:77], v[100:101]
	v_pk_fma_f32 v[98:99], v[52:53], v[78:79], v[98:99]
	v_pk_fma_f32 v[76:77], v[10:11], v[78:79], v[76:77]
	v_add_f32_e32 v97, v98, v99
	v_add_f32_e32 v75, v76, v77
	v_add_u32_e32 v76, 0x14000, v103
	ds_read_b128 v[76:79], v76
	s_waitcnt lgkmcnt(0)
	v_pk_fma_f32 v[98:99], v[4:5], v[76:77], 0 op_sel_hi:[1,1,0]
	v_pk_fma_f32 v[76:77], v[58:59], v[76:77], 0 op_sel_hi:[1,1,0]
	v_pk_fma_f32 v[98:99], v[2:3], v[78:79], v[98:99]
	v_pk_fma_f32 v[100:101], v[56:57], v[78:79], v[76:77]
	v_add_u32_e32 v76, 0x14400, v103
	ds_read_b128 v[76:79], v76
	s_waitcnt lgkmcnt(0)
	v_pk_fma_f32 v[98:99], v[8:9], v[76:77], v[98:99]
	v_pk_fma_f32 v[76:77], v[66:67], v[76:77], v[100:101]
	v_pk_fma_f32 v[98:99], v[6:7], v[78:79], v[98:99]
	v_pk_fma_f32 v[100:101], v[62:63], v[78:79], v[76:77]
	v_add_u32_e32 v76, 0x14800, v103
	ds_read_b128 v[76:79], v76
	s_waitcnt lgkmcnt(0)
	v_pk_fma_f32 v[98:99], v[34:35], v[76:77], v[98:99]
	v_pk_fma_f32 v[76:77], v[70:71], v[76:77], v[100:101]
	v_pk_fma_f32 v[98:99], v[32:33], v[78:79], v[98:99]
	v_pk_fma_f32 v[100:101], v[68:69], v[78:79], v[76:77]
	v_add_u32_e32 v76, 0x14c00, v103
	ds_read_b128 v[76:79], v76
	s_waitcnt lgkmcnt(0)
	v_pk_fma_f32 v[98:99], v[38:39], v[76:77], v[98:99]
	v_pk_fma_f32 v[76:77], v[30:31], v[76:77], v[100:101]
	v_pk_fma_f32 v[98:99], v[36:37], v[78:79], v[98:99]
	v_pk_fma_f32 v[100:101], v[28:29], v[78:79], v[76:77]
	v_add_u32_e32 v76, 0x15000, v103
	ds_read_b128 v[76:79], v76
	s_waitcnt lgkmcnt(0)
	v_pk_fma_f32 v[98:99], v[42:43], v[76:77], v[98:99]
	v_pk_fma_f32 v[76:77], v[22:23], v[76:77], v[100:101]
	v_pk_fma_f32 v[98:99], v[40:41], v[78:79], v[98:99]
	v_pk_fma_f32 v[100:101], v[20:21], v[78:79], v[76:77]
	v_add_u32_e32 v76, 0x15400, v103
	ds_read_b128 v[76:79], v76
	s_waitcnt lgkmcnt(0)
	v_pk_fma_f32 v[98:99], v[46:47], v[76:77], v[98:99]
	v_pk_fma_f32 v[76:77], v[26:27], v[76:77], v[100:101]
	v_pk_fma_f32 v[98:99], v[44:45], v[78:79], v[98:99]
	v_pk_fma_f32 v[100:101], v[24:25], v[78:79], v[76:77]
	v_add_u32_e32 v76, 0x15800, v103
	ds_read_b128 v[76:79], v76
	s_waitcnt lgkmcnt(0)
	v_pk_fma_f32 v[98:99], v[50:51], v[76:77], v[98:99]
	v_pk_fma_f32 v[76:77], v[18:19], v[76:77], v[100:101]
	v_pk_fma_f32 v[98:99], v[48:49], v[78:79], v[98:99]
	v_pk_fma_f32 v[100:101], v[16:17], v[78:79], v[76:77]
	v_add_u32_e32 v76, 0x15c00, v103
	ds_read_b128 v[76:79], v76
	s_waitcnt lgkmcnt(0)
	v_pk_fma_f32 v[98:99], v[54:55], v[76:77], v[98:99]
	v_pk_fma_f32 v[76:77], v[12:13], v[76:77], v[100:101]
	v_pk_fma_f32 v[98:99], v[52:53], v[78:79], v[98:99]
	v_pk_fma_f32 v[76:77], v[10:11], v[78:79], v[76:77]
	v_add_f32_e32 v98, v98, v99
	v_add_f32_e32 v76, v76, v77
	v_add_u32_e32 v77, 0x16000, v103
	ds_read_b128 v[104:107], v77
	v_add_u32_e32 v77, 0x16400, v103
	s_waitcnt lgkmcnt(0)
	v_pk_fma_f32 v[78:79], v[4:5], v[104:105], 0 op_sel_hi:[1,1,0]
	v_pk_fma_f32 v[100:101], v[58:59], v[104:105], 0 op_sel_hi:[1,1,0]
	v_pk_fma_f32 v[78:79], v[2:3], v[106:107], v[78:79]
	v_pk_fma_f32 v[100:101], v[56:57], v[106:107], v[100:101]
	ds_read_b128 v[104:107], v77
	v_add_u32_e32 v77, 0x16800, v103
	s_waitcnt lgkmcnt(0)
	v_pk_fma_f32 v[78:79], v[8:9], v[104:105], v[78:79]
	v_pk_fma_f32 v[100:101], v[66:67], v[104:105], v[100:101]
	v_pk_fma_f32 v[78:79], v[6:7], v[106:107], v[78:79]
	v_pk_fma_f32 v[100:101], v[62:63], v[106:107], v[100:101]
	ds_read_b128 v[104:107], v77
	v_add_u32_e32 v77, 0x16c00, v103
	s_waitcnt lgkmcnt(0)
	v_pk_fma_f32 v[78:79], v[34:35], v[104:105], v[78:79]
	v_pk_fma_f32 v[100:101], v[70:71], v[104:105], v[100:101]
	v_pk_fma_f32 v[78:79], v[32:33], v[106:107], v[78:79]
	v_pk_fma_f32 v[100:101], v[68:69], v[106:107], v[100:101]
	ds_read_b128 v[104:107], v77
	v_add_u32_e32 v77, 0x17000, v103
	s_waitcnt lgkmcnt(0)
	v_pk_fma_f32 v[78:79], v[38:39], v[104:105], v[78:79]
	v_pk_fma_f32 v[100:101], v[30:31], v[104:105], v[100:101]
	v_pk_fma_f32 v[78:79], v[36:37], v[106:107], v[78:79]
	v_pk_fma_f32 v[100:101], v[28:29], v[106:107], v[100:101]
	ds_read_b128 v[104:107], v77
	v_add_u32_e32 v77, 0x17400, v103
	s_waitcnt lgkmcnt(0)
	v_pk_fma_f32 v[78:79], v[42:43], v[104:105], v[78:79]
	v_pk_fma_f32 v[100:101], v[22:23], v[104:105], v[100:101]
	v_pk_fma_f32 v[78:79], v[40:41], v[106:107], v[78:79]
	v_pk_fma_f32 v[100:101], v[20:21], v[106:107], v[100:101]
	ds_read_b128 v[104:107], v77
	v_add_u32_e32 v77, 0x17800, v103
	s_waitcnt lgkmcnt(0)
	v_pk_fma_f32 v[78:79], v[46:47], v[104:105], v[78:79]
	v_pk_fma_f32 v[100:101], v[26:27], v[104:105], v[100:101]
	v_pk_fma_f32 v[78:79], v[44:45], v[106:107], v[78:79]
	v_pk_fma_f32 v[100:101], v[24:25], v[106:107], v[100:101]
	ds_read_b128 v[104:107], v77
	v_add_u32_e32 v77, 0x17c00, v103
	s_waitcnt lgkmcnt(0)
	v_pk_fma_f32 v[78:79], v[50:51], v[104:105], v[78:79]
	v_pk_fma_f32 v[100:101], v[18:19], v[104:105], v[100:101]
	v_pk_fma_f32 v[78:79], v[48:49], v[106:107], v[78:79]
	v_pk_fma_f32 v[100:101], v[16:17], v[106:107], v[100:101]
	ds_read_b128 v[104:107], v77
	s_waitcnt lgkmcnt(0)
	v_pk_fma_f32 v[78:79], v[54:55], v[104:105], v[78:79]
	v_pk_fma_f32 v[100:101], v[12:13], v[104:105], v[100:101]
	v_pk_fma_f32 v[78:79], v[52:53], v[106:107], v[78:79]
	v_pk_fma_f32 v[100:101], v[10:11], v[106:107], v[100:101]
	v_add_f32_e32 v99, v78, v79
	v_add_f32_e32 v77, v100, v101
	v_add_u32_e32 v78, 0x18000, v103
	ds_read_b128 v[104:107], v78
	s_waitcnt lgkmcnt(0)
	v_pk_fma_f32 v[78:79], v[4:5], v[104:105], 0 op_sel_hi:[1,1,0]
	v_pk_fma_f32 v[100:101], v[58:59], v[104:105], 0 op_sel_hi:[1,1,0]
	v_pk_fma_f32 v[78:79], v[2:3], v[106:107], v[78:79]
	v_pk_fma_f32 v[100:101], v[56:57], v[106:107], v[100:101]
	ds_read_b128 v[104:107], v80
	v_add_u32_e32 v80, 0x18800, v103
	s_waitcnt lgkmcnt(0)
	v_pk_fma_f32 v[78:79], v[8:9], v[104:105], v[78:79]
	v_pk_fma_f32 v[100:101], v[66:67], v[104:105], v[100:101]
	v_pk_fma_f32 v[78:79], v[6:7], v[106:107], v[78:79]
	v_pk_fma_f32 v[100:101], v[62:63], v[106:107], v[100:101]
	ds_read_b128 v[104:107], v80
	v_add_u32_e32 v80, 0x18c00, v103
	s_waitcnt lgkmcnt(0)
	v_pk_fma_f32 v[78:79], v[34:35], v[104:105], v[78:79]
	v_pk_fma_f32 v[100:101], v[70:71], v[104:105], v[100:101]
	v_pk_fma_f32 v[78:79], v[32:33], v[106:107], v[78:79]
	v_pk_fma_f32 v[100:101], v[68:69], v[106:107], v[100:101]
	ds_read_b128 v[104:107], v80
	v_add_u32_e32 v80, 0x19000, v103
	s_waitcnt lgkmcnt(0)
	v_pk_fma_f32 v[78:79], v[38:39], v[104:105], v[78:79]
	v_pk_fma_f32 v[100:101], v[30:31], v[104:105], v[100:101]
	v_pk_fma_f32 v[78:79], v[36:37], v[106:107], v[78:79]
	v_pk_fma_f32 v[100:101], v[28:29], v[106:107], v[100:101]
	ds_read_b128 v[104:107], v80
	v_add_u32_e32 v80, 0x19400, v103
	s_waitcnt lgkmcnt(0)
	v_pk_fma_f32 v[78:79], v[42:43], v[104:105], v[78:79]
	v_pk_fma_f32 v[100:101], v[22:23], v[104:105], v[100:101]
	v_pk_fma_f32 v[78:79], v[40:41], v[106:107], v[78:79]
	v_pk_fma_f32 v[100:101], v[20:21], v[106:107], v[100:101]
	ds_read_b128 v[104:107], v80
	v_add_u32_e32 v80, 0x19800, v103
	s_waitcnt lgkmcnt(0)
	v_pk_fma_f32 v[78:79], v[46:47], v[104:105], v[78:79]
	v_pk_fma_f32 v[100:101], v[26:27], v[104:105], v[100:101]
	v_pk_fma_f32 v[78:79], v[44:45], v[106:107], v[78:79]
	v_pk_fma_f32 v[100:101], v[24:25], v[106:107], v[100:101]
	ds_read_b128 v[104:107], v80
	v_add_u32_e32 v80, 0x19c00, v103
	s_waitcnt lgkmcnt(0)
	v_pk_fma_f32 v[78:79], v[50:51], v[104:105], v[78:79]
	v_pk_fma_f32 v[100:101], v[18:19], v[104:105], v[100:101]
	v_pk_fma_f32 v[78:79], v[48:49], v[106:107], v[78:79]
	v_pk_fma_f32 v[100:101], v[16:17], v[106:107], v[100:101]
	ds_read_b128 v[104:107], v80
	v_add_u32_e32 v80, 0x1c000, v103
	s_waitcnt lgkmcnt(0)
	v_pk_fma_f32 v[78:79], v[54:55], v[104:105], v[78:79]
	v_pk_fma_f32 v[100:101], v[12:13], v[104:105], v[100:101]
	v_pk_fma_f32 v[78:79], v[52:53], v[106:107], v[78:79]
	v_pk_fma_f32 v[104:105], v[10:11], v[106:107], v[100:101]
	v_add_f32_e32 v100, v78, v79
	v_add_f32_e32 v78, v104, v105
	v_add_u32_e32 v79, 0x1a000, v103
	ds_read_b128 v[104:107], v79
	v_add_u32_e32 v79, 0x1a400, v103
	s_waitcnt lgkmcnt(0)
	v_pk_fma_f32 v[108:109], v[4:5], v[104:105], 0 op_sel_hi:[1,1,0]
	v_pk_fma_f32 v[104:105], v[58:59], v[104:105], 0 op_sel_hi:[1,1,0]
	v_pk_fma_f32 v[108:109], v[2:3], v[106:107], v[108:109]
	v_pk_fma_f32 v[110:111], v[56:57], v[106:107], v[104:105]
	ds_read_b128 v[104:107], v79
	v_add_u32_e32 v79, 0x1a800, v103
	s_waitcnt lgkmcnt(0)
	v_pk_fma_f32 v[108:109], v[8:9], v[104:105], v[108:109]
	v_pk_fma_f32 v[104:105], v[66:67], v[104:105], v[110:111]
	v_pk_fma_f32 v[108:109], v[6:7], v[106:107], v[108:109]
	v_pk_fma_f32 v[110:111], v[62:63], v[106:107], v[104:105]
	ds_read_b128 v[104:107], v79
	v_add_u32_e32 v79, 0x1ac00, v103
	s_waitcnt lgkmcnt(0)
	v_pk_fma_f32 v[108:109], v[34:35], v[104:105], v[108:109]
	v_pk_fma_f32 v[104:105], v[70:71], v[104:105], v[110:111]
	v_pk_fma_f32 v[108:109], v[32:33], v[106:107], v[108:109]
	v_pk_fma_f32 v[110:111], v[68:69], v[106:107], v[104:105]
	ds_read_b128 v[104:107], v79
	v_add_u32_e32 v79, 0x1b000, v103
	s_waitcnt lgkmcnt(0)
	v_pk_fma_f32 v[108:109], v[38:39], v[104:105], v[108:109]
	v_pk_fma_f32 v[104:105], v[30:31], v[104:105], v[110:111]
	v_pk_fma_f32 v[108:109], v[36:37], v[106:107], v[108:109]
	v_pk_fma_f32 v[110:111], v[28:29], v[106:107], v[104:105]
	ds_read_b128 v[104:107], v79
	v_add_u32_e32 v79, 0x1b400, v103
	s_waitcnt lgkmcnt(0)
	v_pk_fma_f32 v[108:109], v[42:43], v[104:105], v[108:109]
	v_pk_fma_f32 v[104:105], v[22:23], v[104:105], v[110:111]
	v_pk_fma_f32 v[108:109], v[40:41], v[106:107], v[108:109]
	v_pk_fma_f32 v[110:111], v[20:21], v[106:107], v[104:105]
	ds_read_b128 v[104:107], v79
	v_add_u32_e32 v79, 0x1b800, v103
	s_waitcnt lgkmcnt(0)
	v_pk_fma_f32 v[108:109], v[46:47], v[104:105], v[108:109]
	v_pk_fma_f32 v[104:105], v[26:27], v[104:105], v[110:111]
	v_pk_fma_f32 v[108:109], v[44:45], v[106:107], v[108:109]
	v_pk_fma_f32 v[110:111], v[24:25], v[106:107], v[104:105]
	ds_read_b128 v[104:107], v79
	v_add_u32_e32 v79, 0x1bc00, v103
	s_waitcnt lgkmcnt(0)
	v_pk_fma_f32 v[108:109], v[50:51], v[104:105], v[108:109]
	v_pk_fma_f32 v[104:105], v[18:19], v[104:105], v[110:111]
	v_pk_fma_f32 v[108:109], v[48:49], v[106:107], v[108:109]
	v_pk_fma_f32 v[110:111], v[16:17], v[106:107], v[104:105]
	ds_read_b128 v[104:107], v79
	s_waitcnt lgkmcnt(0)
	v_pk_fma_f32 v[108:109], v[54:55], v[104:105], v[108:109]
	v_pk_fma_f32 v[104:105], v[12:13], v[104:105], v[110:111]
	v_pk_fma_f32 v[108:109], v[52:53], v[106:107], v[108:109]
	v_pk_fma_f32 v[104:105], v[10:11], v[106:107], v[104:105]
	v_add_f32_e32 v101, v108, v109
	v_add_f32_e32 v79, v104, v105
	ds_read_b128 v[104:107], v80
	v_add_u32_e32 v80, 0x1c400, v103
	s_waitcnt lgkmcnt(0)
	v_pk_fma_f32 v[108:109], v[4:5], v[104:105], 0 op_sel_hi:[1,1,0]
	v_pk_fma_f32 v[104:105], v[58:59], v[104:105], 0 op_sel_hi:[1,1,0]
	v_pk_fma_f32 v[108:109], v[2:3], v[106:107], v[108:109]
	v_pk_fma_f32 v[110:111], v[56:57], v[106:107], v[104:105]
	ds_read_b128 v[104:107], v80
	v_add_u32_e32 v80, 0x1c800, v103
	s_waitcnt lgkmcnt(0)
	v_pk_fma_f32 v[108:109], v[8:9], v[104:105], v[108:109]
	v_pk_fma_f32 v[104:105], v[66:67], v[104:105], v[110:111]
	v_pk_fma_f32 v[108:109], v[6:7], v[106:107], v[108:109]
	v_pk_fma_f32 v[110:111], v[62:63], v[106:107], v[104:105]
	ds_read_b128 v[104:107], v80
	v_add_u32_e32 v80, 0x1cc00, v103
	s_waitcnt lgkmcnt(0)
	v_pk_fma_f32 v[108:109], v[34:35], v[104:105], v[108:109]
	v_pk_fma_f32 v[104:105], v[70:71], v[104:105], v[110:111]
	v_pk_fma_f32 v[108:109], v[32:33], v[106:107], v[108:109]
	v_pk_fma_f32 v[110:111], v[68:69], v[106:107], v[104:105]
	ds_read_b128 v[104:107], v80
	v_add_u32_e32 v80, 0x1d000, v103
	s_waitcnt lgkmcnt(0)
	v_pk_fma_f32 v[108:109], v[38:39], v[104:105], v[108:109]
	v_pk_fma_f32 v[104:105], v[30:31], v[104:105], v[110:111]
	v_pk_fma_f32 v[108:109], v[36:37], v[106:107], v[108:109]
	v_pk_fma_f32 v[110:111], v[28:29], v[106:107], v[104:105]
	ds_read_b128 v[104:107], v80
	v_add_u32_e32 v80, 0x1d400, v103
	s_waitcnt lgkmcnt(0)
	v_pk_fma_f32 v[108:109], v[42:43], v[104:105], v[108:109]
	v_pk_fma_f32 v[104:105], v[22:23], v[104:105], v[110:111]
	v_pk_fma_f32 v[108:109], v[40:41], v[106:107], v[108:109]
	v_pk_fma_f32 v[110:111], v[20:21], v[106:107], v[104:105]
	ds_read_b128 v[104:107], v80
	v_add_u32_e32 v80, 0x1d800, v103
	s_waitcnt lgkmcnt(0)
	v_pk_fma_f32 v[108:109], v[46:47], v[104:105], v[108:109]
	v_pk_fma_f32 v[104:105], v[26:27], v[104:105], v[110:111]
	v_pk_fma_f32 v[108:109], v[44:45], v[106:107], v[108:109]
	v_pk_fma_f32 v[110:111], v[24:25], v[106:107], v[104:105]
	ds_read_b128 v[104:107], v80
	v_add_u32_e32 v80, 0x1dc00, v103
	s_waitcnt lgkmcnt(0)
	v_pk_fma_f32 v[108:109], v[50:51], v[104:105], v[108:109]
	v_pk_fma_f32 v[104:105], v[18:19], v[104:105], v[110:111]
	v_pk_fma_f32 v[108:109], v[48:49], v[106:107], v[108:109]
	v_pk_fma_f32 v[110:111], v[16:17], v[106:107], v[104:105]
	ds_read_b128 v[104:107], v80
	s_waitcnt lgkmcnt(0)
	v_pk_fma_f32 v[108:109], v[54:55], v[104:105], v[108:109]
	v_pk_fma_f32 v[104:105], v[12:13], v[104:105], v[110:111]
	v_pk_fma_f32 v[108:109], v[52:53], v[106:107], v[108:109]
	v_pk_fma_f32 v[104:105], v[10:11], v[106:107], v[104:105]
	v_add_f32_e32 v102, v108, v109
	v_add_f32_e32 v80, v104, v105
	v_add_u32_e32 v104, 0x1e000, v103
	ds_read_b128 v[104:107], v104
	s_waitcnt lgkmcnt(0)
	v_pk_fma_f32 v[4:5], v[4:5], v[104:105], 0 op_sel_hi:[1,1,0]
	s_nop 0
	v_pk_fma_f32 v[108:109], v[2:3], v[106:107], v[4:5]
	v_pk_fma_f32 v[2:3], v[58:59], v[104:105], 0 op_sel_hi:[1,1,0]
	s_nop 0
	v_pk_fma_f32 v[56:57], v[56:57], v[106:107], v[2:3]
	v_add_u32_e32 v2, 0x1e400, v103
	ds_read_b128 v[2:5], v2
	s_waitcnt lgkmcnt(0)
	v_pk_fma_f32 v[8:9], v[8:9], v[2:3], v[108:109]
	v_pk_fma_f32 v[2:3], v[66:67], v[2:3], v[56:57]
	v_pk_fma_f32 v[6:7], v[6:7], v[4:5], v[8:9]
	v_pk_fma_f32 v[8:9], v[62:63], v[4:5], v[2:3]
	v_add_u32_e32 v2, 0x1e800, v103
	ds_read_b128 v[2:5], v2
	s_waitcnt lgkmcnt(0)
	v_pk_fma_f32 v[6:7], v[34:35], v[2:3], v[6:7]
	v_pk_fma_f32 v[2:3], v[70:71], v[2:3], v[8:9]
	v_pk_fma_f32 v[6:7], v[32:33], v[4:5], v[6:7]
	v_pk_fma_f32 v[8:9], v[68:69], v[4:5], v[2:3]
	v_add_u32_e32 v2, 0x1ec00, v103
	ds_read_b128 v[2:5], v2
	s_waitcnt lgkmcnt(0)
	v_pk_fma_f32 v[6:7], v[38:39], v[2:3], v[6:7]
	v_pk_fma_f32 v[2:3], v[30:31], v[2:3], v[8:9]
	v_pk_fma_f32 v[6:7], v[36:37], v[4:5], v[6:7]
	v_pk_fma_f32 v[8:9], v[28:29], v[4:5], v[2:3]
	v_add_u32_e32 v2, 0x1f000, v103
	ds_read_b128 v[2:5], v2
	s_waitcnt lgkmcnt(0)
	v_pk_fma_f32 v[6:7], v[42:43], v[2:3], v[6:7]
	v_pk_fma_f32 v[2:3], v[22:23], v[2:3], v[8:9]
	v_pk_fma_f32 v[6:7], v[40:41], v[4:5], v[6:7]
	v_pk_fma_f32 v[8:9], v[20:21], v[4:5], v[2:3]
	v_add_u32_e32 v2, 0x1f400, v103
	ds_read_b128 v[2:5], v2
	s_waitcnt lgkmcnt(0)
	v_pk_fma_f32 v[6:7], v[46:47], v[2:3], v[6:7]
	v_pk_fma_f32 v[2:3], v[26:27], v[2:3], v[8:9]
	v_pk_fma_f32 v[6:7], v[44:45], v[4:5], v[6:7]
	v_pk_fma_f32 v[8:9], v[24:25], v[4:5], v[2:3]
	v_add_u32_e32 v2, 0x1f800, v103
	ds_read_b128 v[2:5], v2
	s_waitcnt lgkmcnt(0)
	v_pk_fma_f32 v[6:7], v[50:51], v[2:3], v[6:7]
	v_pk_fma_f32 v[2:3], v[18:19], v[2:3], v[8:9]
	v_pk_fma_f32 v[6:7], v[48:49], v[4:5], v[6:7]
	v_pk_fma_f32 v[8:9], v[16:17], v[4:5], v[2:3]
	v_add_u32_e32 v2, 0x1fc00, v103
	ds_read_b128 v[2:5], v2
	s_waitcnt lgkmcnt(0)
	v_pk_fma_f32 v[6:7], v[54:55], v[2:3], v[6:7]
	v_pk_fma_f32 v[2:3], v[12:13], v[2:3], v[8:9]
	v_pk_fma_f32 v[6:7], v[52:53], v[4:5], v[6:7]
	v_pk_fma_f32 v[4:5], v[10:11], v[4:5], v[2:3]
	v_and_b32_e32 v3, 32, v1
	v_cmp_eq_u32_e32 vcc, 0, v3
	v_add_f32_e32 v4, v4, v5
	v_add_f32_e32 v2, v6, v7
	v_cndmask_b32_e32 v5, v81, v96, vcc
	ds_bpermute_b32 v5, v95, v5
	v_cndmask_b32_e32 v6, v82, v97, vcc
	ds_bpermute_b32 v6, v95, v6
	v_cndmask_b32_e32 v7, v84, v98, vcc
	ds_bpermute_b32 v7, v95, v7
	v_cndmask_b32_e32 v8, v85, v99, vcc
	ds_bpermute_b32 v8, v95, v8
	v_cndmask_b32_e32 v9, v86, v100, vcc
	v_cndmask_b32_e32 v3, v96, v81, vcc
	ds_bpermute_b32 v9, v95, v9
	v_cndmask_b32_e32 v10, v87, v101, vcc
	s_waitcnt lgkmcnt(4)
	v_add_f32_e32 v3, v3, v5
	v_cndmask_b32_e32 v5, v97, v82, vcc
	ds_bpermute_b32 v10, v95, v10
	v_cndmask_b32_e32 v11, v88, v102, vcc
	s_waitcnt lgkmcnt(4)
	v_add_f32_e32 v6, v5, v6
	v_cndmask_b32_e32 v5, v98, v84, vcc
	ds_bpermute_b32 v11, v95, v11
	s_waitcnt lgkmcnt(4)
	v_add_f32_e32 v7, v5, v7
	v_cndmask_b32_e32 v5, v99, v85, vcc
	s_waitcnt lgkmcnt(3)
	v_add_f32_e32 v8, v5, v8
	v_cndmask_b32_e32 v5, v100, v86, vcc
	s_waitcnt lgkmcnt(2)
	v_add_f32_e32 v5, v5, v9
	v_cndmask_b32_e32 v9, v101, v87, vcc
	s_waitcnt lgkmcnt(1)
	v_add_f32_e32 v9, v9, v10
	v_cndmask_b32_e32 v10, v102, v88, vcc
	s_waitcnt lgkmcnt(0)
	v_add_f32_e32 v10, v10, v11
	v_cndmask_b32_e32 v11, v2, v89, vcc
	v_cndmask_b32_e32 v2, v89, v2, vcc
	ds_bpermute_b32 v2, v95, v2
	s_waitcnt lgkmcnt(0)
	v_add_f32_e32 v11, v11, v2
	v_and_b32_e32 v2, 16, v1
	v_cmp_eq_u32_e64 s[10:11], 0, v2
	s_nop 1
	v_cndmask_b32_e64 v2, v5, v3, s[10:11]
	v_cndmask_b32_e64 v3, v3, v5, s[10:11]
	ds_bpermute_b32 v3, v94, v3
	s_waitcnt lgkmcnt(0)
	v_add_f32_e32 v5, v2, v3
	v_cndmask_b32_e64 v3, v6, v9, s[10:11]
	ds_bpermute_b32 v3, v94, v3
	v_cndmask_b32_e64 v2, v9, v6, s[10:11]
	v_cndmask_b32_e64 v6, v7, v10, s[10:11]
	ds_bpermute_b32 v6, v94, v6
	s_waitcnt lgkmcnt(1)
	v_add_f32_e32 v2, v2, v3
	v_cndmask_b32_e64 v3, v10, v7, s[10:11]
	v_cndmask_b32_e64 v7, v8, v11, s[10:11]
	ds_bpermute_b32 v7, v94, v7
	s_waitcnt lgkmcnt(1)
	v_add_f32_e32 v6, v3, v6
	v_cndmask_b32_e64 v3, v11, v8, s[10:11]
	s_waitcnt lgkmcnt(0)
	v_add_f32_e32 v3, v3, v7
	v_and_b32_e32 v7, 8, v1
	v_cmp_eq_u32_e64 s[12:13], 0, v7
	s_nop 1
	v_cndmask_b32_e64 v7, v6, v5, s[12:13]
	v_cndmask_b32_e64 v5, v5, v6, s[12:13]
	v_cndmask_b32_e64 v6, v3, v2, s[12:13]
	v_cndmask_b32_e64 v2, v2, v3, s[12:13]
	ds_bpermute_b32 v5, v93, v5
	ds_bpermute_b32 v2, v93, v2
	v_and_b32_e32 v3, 4, v1
	v_cmp_eq_u32_e64 s[14:15], 0, v3
	s_waitcnt lgkmcnt(1)
	v_add_f32_e32 v5, v7, v5
	s_waitcnt lgkmcnt(0)
	v_add_f32_e32 v2, v6, v2
	v_cndmask_b32_e64 v3, v2, v5, s[14:15]
	v_cndmask_b32_e64 v2, v5, v2, s[14:15]
	ds_bpermute_b32 v2, v92, v2
	v_and_b32_e32 v5, 3, v1
	v_bfe_u32 v1, v1, 2, 4
	v_cmp_eq_u32_e64 s[16:17], 0, v5
	v_lshlrev_b32_e32 v82, 2, v1
	s_waitcnt lgkmcnt(0)
	v_add_f32_e32 v2, v3, v2
	ds_bpermute_b32 v3, v91, v2
	s_waitcnt lgkmcnt(0)
	v_add_f32_e32 v2, v2, v3
	ds_bpermute_b32 v3, v90, v2
	s_and_saveexec_b64 s[40:41], s[16:17]
	s_cbranch_execz .LBB0_1749
	s_waitcnt lgkmcnt(0)
	v_add_f32_e32 v2, v2, v3
	global_load_dword v3, v82, s[38:39] offset:64
	v_cmp_lt_u32_e64 s[18:19], 7, v1
	s_waitcnt vmcnt(0)
	v_add_f32_e32 v5, v2, v3
	s_and_saveexec_b64 s[8:9], s[18:19]
	s_xor_b64 s[54:55], exec, s[8:9]
	s_cbranch_execz .LBB0_1746
	s_mov_b32 s18, 0xbfb8aa3b
	v_mul_f32_e64 v2, |v5|, s18
	v_exp_f32_e32 v6, v2
	s_lshl_b64 s[8:9], s[30:31], 5
	s_add_u32 s8, s58, s8
	s_addc_u32 s9, s59, s9
	v_lshl_add_u64 v[2:3], s[8:9], 0, v[82:83]
	v_add_f32_e32 v6, 1.0, v6
	s_mov_b32 s8, 0x800000
	v_cmp_gt_f32_e64 s[18:19], s8, v6
	s_movk_i32 s8, 0xffe0
	s_mov_b32 s9, -1
	v_cndmask_b32_e64 v7, 0, 32, s[18:19]
	v_ldexp_f32 v6, v6, v7
	v_log_f32_e32 v6, v6
	v_lshl_add_u64 v[2:3], v[2:3], 0, s[8:9]
	s_mov_b32 s8, 0x3f317217
	v_max_f32_e32 v5, v5, v5
	v_mul_f32_e32 v7, 0x3f317217, v6
	v_fma_f32 v7, v6, s8, -v7
	v_fmac_f32_e32 v7, 0x3377d1cf, v6
	s_mov_b32 s8, 0x7f800000
	v_fmac_f32_e32 v7, 0x3f317217, v6
	v_cmp_lt_f32_e64 s[20:21], |v6|, s8
	v_min_f32_e32 v5, 0, v5
	s_nop 0
	v_cndmask_b32_e64 v6, v6, v7, s[20:21]
	v_mov_b32_e32 v7, 0x41b17218
	v_cndmask_b32_e64 v7, 0, v7, s[18:19]
	v_sub_f32_e32 v6, v6, v7
	v_sub_f32_e32 v5, v5, v6
